# S5 scans: B*u on v_mfma_f32_16x16x4_f32 (f32 in/acc) + LDS transpose + 6-op VALU recurrence; wave-item remap for row locality; batched C loads
# speedup vs baseline: 1.0570x; 1.0310x over previous
.LBB0_504:
	v_mov_b32_e32 v56, v163
	v_lshl_add_u32 v0, s2, 8, v60
	v_bfe_u32 v68, v56, 6, 2
	v_or_b32_e32 v54, v68, v0
	s_mov_b32 s3, 0x3c3c3c4
	v_lshrrev_b32_e32 v70, 5, v54
	v_and_b32_e32 v71, 31, v54
	v_mul_hi_u32 v63, v70, s3
	v_mul_u32_u24_e32 v0, 0x44, v63
	v_sub_u32_e32 v70, v70, v0
	v_lshl_or_b32 v71, v63, 5, v71
	v_mul_u32_u24_e32 v71, 0x44, v71
	v_add_u32_e32 v54, v71, v70
	s_mov_b32 s3, 0x78787879
	v_mul_hi_i32 v70, v54, s3
	v_ashrrev_i32_e32 v0, 5, v70
	v_lshrrev_b32_e32 v71, 31, v70
	v_add_u32_e32 v63, v0, v71
	v_lshrrev_b32_e32 v0, 10, v70
	v_add_u32_e32 v0, v0, v71
	v_readlane_b32 s56, v252, 0
	v_and_b32_e32 v59, 31, v63
	v_and_b32_e32 v69, 1, v0
	v_readlane_b32 s60, v252, 4
	v_readlane_b32 s61, v252, 5
	v_readlane_b32 s62, v252, 6
	v_readlane_b32 s63, v252, 7
	v_readlane_b32 s64, v252, 8
	v_readlane_b32 s65, v252, 9
	v_readlane_b32 s66, v252, 10
	v_readlane_b32 s67, v252, 11
	v_readlane_b32 s68, v252, 12
	v_readlane_b32 s69, v252, 13
	v_readlane_b32 s70, v252, 14
	v_readlane_b32 s71, v252, 15
	v_and_b32_e32 v57, 63, v56
	s_waitcnt vmcnt(10)
	v_lshl_or_b32 v36, v69, 5, v59
	v_ashrrev_i32_e32 v55, 31, v54
	v_readlane_b32 s60, v252, 16
	v_lshl_or_b32 v0, v36, 6, v57
	s_waitcnt vmcnt(0)
	v_lshlrev_b64 v[18:19], 9, v[54:55]
	v_readlane_b32 s68, v252, 24
	v_readlane_b32 s69, v252, 25
	v_lshlrev_b32_e32 v20, 3, v0
	v_and_b32_e32 v134, 48, v0
	v_lshlrev_b32_e32 v134, 1, v134
	v_and_b32_e32 v30, 0xffffffcf, v0
	v_lshl_or_b32 v30, v30, 7, v134
	v_add_u32_e32 v134, 0x1000, v30
	v_lshl_add_u64 v[18:19], s[68:69], 0, v[18:19]
	v_lshlrev_b32_e32 v0, 3, v57
	v_readlane_b32 s40, v254, 55
	v_and_b32_e32 v72, 15, v56
	v_readlane_b32 s57, v252, 1
	v_lshl_add_u64 v[34:35], v[18:19], 0, v[0:1]
	v_readlane_b32 s41, v254, 56
	v_readlane_b32 s42, v254, 57
	v_readlane_b32 s43, v254, 58
	v_readlane_b32 s44, v254, 59
	v_readlane_b32 s45, v254, 60
	v_readlane_b32 s46, v254, 61
	v_readlane_b32 s47, v254, 62
	v_readlane_b32 s48, v254, 63
	v_readlane_b32 s49, v255, 0
	v_readlane_b32 s50, v255, 1
	v_readlane_b32 s51, v255, 2
	v_readlane_b32 s52, v255, 3
	v_readlane_b32 s53, v255, 4
	v_readlane_b32 s54, v255, 5
	v_readlane_b32 s55, v255, 6
	v_lshlrev_b32_e32 v0, 8, v72
	global_load_dwordx4 v[2:5], v30, s[56:57]
	global_load_dwordx4 v[6:9], v30, s[56:57] offset:16
	s_waitcnt lgkmcnt(0)
	global_load_dwordx4 v[10:13], v30, s[56:57] offset:2048
	global_load_dwordx4 v[14:17], v30, s[56:57] offset:2064
	global_load_dwordx2 v[50:51], v20, s[54:55]
	s_nop 0
	global_load_dwordx4 v[18:21], v134, s[56:57]
	global_load_dwordx4 v[22:25], v134, s[56:57] offset:16
	global_load_dwordx4 v[26:29], v134, s[56:57] offset:2048
	s_nop 0
	global_load_dwordx4 v[30:33], v134, s[56:57] offset:2064
	s_nop 0
	global_load_dwordx2 v[52:53], v[34:35], off
	v_lshl_or_b32 v0, v36, 12, v0
	v_readlane_b32 s40, v253, 12
	v_lshrrev_b32_e32 v36, 2, v56
	v_readlane_b32 s50, v253, 22
	v_readlane_b32 s51, v253, 23
	v_and_b32_e32 v62, 12, v36
	v_readlane_b32 s52, v253, 24
	v_readlane_b32 s53, v253, 25
	v_lshl_add_u64 v[34:35], s[50:51], 0, v[0:1]
	v_lshlrev_b32_e32 v36, 2, v62
	v_mov_b32_e32 v37, v1
	v_lshl_add_u64 v[64:65], v[34:35], 0, v[36:37]
	v_lshl_add_u64 v[34:35], s[52:53], 0, v[0:1]
	v_lshl_add_u64 v[66:67], v[34:35], 0, v[36:37]
	global_load_dwordx4 v[96:99], v[64:65], off
	global_load_dwordx4 v[100:103], v[66:67], off
	global_load_dwordx4 v[104:107], v[64:65], off offset:64
	global_load_dwordx4 v[108:111], v[66:67], off offset:64
	global_load_dwordx4 v[112:115], v[64:65], off offset:128
	global_load_dwordx4 v[116:119], v[66:67], off offset:128
	global_load_dwordx4 v[120:123], v[64:65], off offset:192
	global_load_dwordx4 v[124:127], v[66:67], off offset:192
	s_movk_i32 s3, 0x44
	s_movk_i32 s4, 0x4880
	v_mad_u32_u24 v58, v68, s4, v222
	v_readlane_b32 s64, v252, 20
	v_readlane_b32 s65, v252, 21
	v_mov_b32_e32 v55, v1
	v_readlane_b32 s66, v252, 22
	v_readlane_b32 s67, v252, 23
	v_cmp_eq_u32_e32 vcc, 0, v69
	v_mad_u32_u24 v68, v68, s4, v61
	v_readlane_b32 s58, v252, 2
	v_readlane_b32 s59, v252, 3
	v_readlane_b32 s61, v252, 17
	v_readlane_b32 s62, v252, 18
	v_readlane_b32 s63, v252, 19
	v_readlane_b32 s70, v252, 26
	v_readlane_b32 s71, v252, 27
	v_readlane_b32 s72, v252, 28
	v_readlane_b32 s73, v252, 29
	v_readlane_b32 s74, v252, 30
	v_readlane_b32 s75, v252, 31
	v_readlane_b32 s41, v253, 13
	v_readlane_b32 s42, v253, 14
	v_readlane_b32 s43, v253, 15
	v_readlane_b32 s44, v253, 16
	v_readlane_b32 s45, v253, 17
	v_readlane_b32 s46, v253, 18
	v_readlane_b32 s47, v253, 19
	v_readlane_b32 s48, v253, 20
	v_readlane_b32 s49, v253, 21
	v_readlane_b32 s54, v253, 26
	v_readlane_b32 s55, v253, 27
	v_mul_lo_u32 v0, v63, s3
	v_sub_u32_e32 v0, v54, v0
	v_ashrrev_i32_e32 v54, 11, v70
	v_add_u32_e32 v54, v54, v71
	v_bfe_u32 v63, v56, 2, 4
	v_mul_i32_i24_e32 v64, 0x1100, v54
	v_lshlrev_b32_e32 v54, 4, v56
	v_lshlrev_b32_e32 v65, 6, v0
	v_lshlrev_b32_e32 v0, 6, v63
	v_and_b32_e32 v54, 48, v54
	v_lshl_add_u32 v67, v57, 2, v58
	s_movk_i32 s3, 0x110
	v_and_b32_e32 v71, 48, v56
	v_lshlrev_b32_e32 v56, 6, v59
	v_mov_b32_e32 v57, v1
	v_add3_u32 v66, v58, v0, v54
	v_mad_u32_u24 v70, v72, s3, v58
	v_lshl_add_u64 v[58:59], s[64:65], 0, v[56:57]
	v_and_b32_e32 v138, 48, v163
	v_mov_b32_e32 v139, v1
	v_lshl_add_u64 v[136:137], v[58:59], 0, v[138:139]
	v_lshl_add_u64 v[54:55], v[58:59], 0, v[54:55]
	v_lshlrev_b32_e32 v58, 2, v72
	v_mov_b32_e32 v59, v1
	v_lshl_add_u64 v[58:59], s[66:67], 0, v[58:59]
	v_mul_u32_u24_e32 v0, 0x8800, v69
	v_lshl_add_u64 v[56:57], v[58:59], 0, v[56:57]
	v_add_u32_e32 v69, v70, v71
	s_mov_b32 s3, 0
	v_and_b32_e32 v140, 15, v163
	v_add_u32_e32 v135, 0, v65
	v_or_b32_e32 v135, v135, v140
	v_cmp_lt_i32_e64 s[4:5], s33, v135
	s_nop 1
	v_cndmask_b32_e64 v142, v205, v206, s[4:5]
	v_sub_u32_e32 v142, v142, v135
	v_cndmask_b32_e32 v135, v142, v135, vcc
	v_add_u32_e32 v142, v135, v64
	v_ashrrev_i32_e32 v143, 31, v142
	v_lshlrev_b64 v[142:143], 11, v[142:143]
	v_lshl_add_u64 v[142:143], v[136:137], 0, v[142:143]
	global_load_dwordx4 v[80:83], v[142:143], off
	v_add_u32_e32 v135, 16, v65
	v_or_b32_e32 v135, v135, v140
	v_cmp_lt_i32_e64 s[4:5], s33, v135
	s_nop 1
	v_cndmask_b32_e64 v142, v205, v206, s[4:5]
	v_sub_u32_e32 v142, v142, v135
	v_cndmask_b32_e32 v135, v142, v135, vcc
	v_add_u32_e32 v142, v135, v64
	v_ashrrev_i32_e32 v143, 31, v142
	v_lshlrev_b64 v[142:143], 11, v[142:143]
	v_lshl_add_u64 v[142:143], v[136:137], 0, v[142:143]
	global_load_dwordx4 v[84:87], v[142:143], off
	v_add_u32_e32 v135, 32, v65
	v_or_b32_e32 v135, v135, v140
	v_cmp_lt_i32_e64 s[4:5], s33, v135
	s_nop 1
	v_cndmask_b32_e64 v142, v205, v206, s[4:5]
	v_sub_u32_e32 v142, v142, v135
	v_cndmask_b32_e32 v135, v142, v135, vcc
	v_add_u32_e32 v142, v135, v64
	v_ashrrev_i32_e32 v143, 31, v142
	v_lshlrev_b64 v[142:143], 11, v[142:143]
	v_lshl_add_u64 v[142:143], v[136:137], 0, v[142:143]
	global_load_dwordx4 v[88:91], v[142:143], off
	v_add_u32_e32 v135, 48, v65
	v_or_b32_e32 v135, v135, v140
	v_cmp_lt_i32_e64 s[4:5], s33, v135
	s_nop 1
	v_cndmask_b32_e64 v142, v205, v206, s[4:5]
	v_sub_u32_e32 v142, v142, v135
	v_cndmask_b32_e32 v135, v142, v135, vcc
	v_add_u32_e32 v142, v135, v64
	v_ashrrev_i32_e32 v143, 31, v142
	v_lshlrev_b64 v[142:143], 11, v[142:143]
	v_lshl_add_u64 v[142:143], v[136:137], 0, v[142:143]
	global_load_dwordx4 v[92:95], v[142:143], off
	s_waitcnt vmcnt(4)
	v_xor_b32_e32 v144, 0x80000000, v100
	v_cvt_pk_bf16_f32 v34, v96, v144
	v_xor_b32_e32 v144, 0x80000000, v101
	v_cvt_pk_bf16_f32 v35, v97, v144
	v_xor_b32_e32 v144, 0x80000000, v102
	v_cvt_pk_bf16_f32 v36, v98, v144
	v_xor_b32_e32 v144, 0x80000000, v103
	v_cvt_pk_bf16_f32 v37, v99, v144
	v_xor_b32_e32 v144, 0x80000000, v108
	v_cvt_pk_bf16_f32 v38, v104, v144
	v_xor_b32_e32 v144, 0x80000000, v109
	v_cvt_pk_bf16_f32 v39, v105, v144
	v_xor_b32_e32 v144, 0x80000000, v110
	v_cvt_pk_bf16_f32 v40, v106, v144
	v_xor_b32_e32 v144, 0x80000000, v111
	v_cvt_pk_bf16_f32 v41, v107, v144
	v_xor_b32_e32 v144, 0x80000000, v116
	v_cvt_pk_bf16_f32 v42, v112, v144
	v_xor_b32_e32 v144, 0x80000000, v117
	v_cvt_pk_bf16_f32 v43, v113, v144
	v_xor_b32_e32 v144, 0x80000000, v118
	v_cvt_pk_bf16_f32 v44, v114, v144
	v_xor_b32_e32 v144, 0x80000000, v119
	v_cvt_pk_bf16_f32 v45, v115, v144
	v_xor_b32_e32 v144, 0x80000000, v124
	v_cvt_pk_bf16_f32 v46, v120, v144
	v_xor_b32_e32 v144, 0x80000000, v125
	v_cvt_pk_bf16_f32 v47, v121, v144
	v_xor_b32_e32 v144, 0x80000000, v126
	v_cvt_pk_bf16_f32 v48, v122, v144
	v_xor_b32_e32 v144, 0x80000000, v127
	v_cvt_pk_bf16_f32 v49, v123, v144
	v_and_b32_e32 v141, 63, v163
	v_and_b32_e32 v132, 48, v163
	s_movk_i32 s3, 0x90
	v_mad_u32_u24 v132, v140, s3, v132
	v_add_u32_e32 v132, v132, v67
	v_lshlrev_b32_e32 v133, 2, v141
	v_sub_u32_e32 v132, v132, v133
	v_add_u32_e32 v132, 0x1100, v132
	s_movk_i32 s4, 0x8c
	v_mad_u32_u24 v133, v141, s4, v67
	v_add_u32_e32 v133, 0x1100, v133
	s_waitcnt vmcnt(3)
	v_mfma_f32_16x16x4_f32 v[96:99], v80, v2, 0
	v_mfma_f32_16x16x4_f32 v[100:103], v80, v3, 0
	v_mfma_f32_16x16x4_f32 v[104:107], v80, v10, 0
	v_mfma_f32_16x16x4_f32 v[108:111], v80, v11, 0
	v_mfma_f32_16x16x4_f32 v[112:115], v80, v18, 0
	v_mfma_f32_16x16x4_f32 v[116:119], v80, v19, 0
	v_mfma_f32_16x16x4_f32 v[120:123], v80, v26, 0
	v_mfma_f32_16x16x4_f32 v[124:127], v80, v27, 0
	v_mfma_f32_16x16x4_f32 v[96:99], v81, v4, v[96:99]
	v_mfma_f32_16x16x4_f32 v[100:103], v81, v5, v[100:103]
	v_mfma_f32_16x16x4_f32 v[104:107], v81, v12, v[104:107]
	v_mfma_f32_16x16x4_f32 v[108:111], v81, v13, v[108:111]
	v_mfma_f32_16x16x4_f32 v[112:115], v81, v20, v[112:115]
	v_mfma_f32_16x16x4_f32 v[116:119], v81, v21, v[116:119]
	v_mfma_f32_16x16x4_f32 v[120:123], v81, v28, v[120:123]
	v_mfma_f32_16x16x4_f32 v[124:127], v81, v29, v[124:127]
	v_mfma_f32_16x16x4_f32 v[96:99], v82, v6, v[96:99]
	v_mfma_f32_16x16x4_f32 v[100:103], v82, v7, v[100:103]
	v_mfma_f32_16x16x4_f32 v[104:107], v82, v14, v[104:107]
	v_mfma_f32_16x16x4_f32 v[108:111], v82, v15, v[108:111]
	v_mfma_f32_16x16x4_f32 v[112:115], v82, v22, v[112:115]
	v_mfma_f32_16x16x4_f32 v[116:119], v82, v23, v[116:119]
	v_mfma_f32_16x16x4_f32 v[120:123], v82, v30, v[120:123]
	v_mfma_f32_16x16x4_f32 v[124:127], v82, v31, v[124:127]
	v_mfma_f32_16x16x4_f32 v[96:99], v83, v8, v[96:99]
	v_mfma_f32_16x16x4_f32 v[100:103], v83, v9, v[100:103]
	v_mfma_f32_16x16x4_f32 v[104:107], v83, v16, v[104:107]
	v_mfma_f32_16x16x4_f32 v[108:111], v83, v17, v[108:111]
	v_mfma_f32_16x16x4_f32 v[112:115], v83, v24, v[112:115]
	v_mfma_f32_16x16x4_f32 v[116:119], v83, v25, v[116:119]
	v_mfma_f32_16x16x4_f32 v[120:123], v83, v32, v[120:123]
	v_mfma_f32_16x16x4_f32 v[124:127], v83, v33, v[124:127]
	s_nop 9
	ds_write_b128 v132, v[96:99]
	ds_write_b128 v132, v[100:103] offset:64
	ds_write_b128 v132, v[104:107] offset:2304
	ds_write_b128 v132, v[108:111] offset:2368
	ds_write_b128 v132, v[112:115] offset:4608
	ds_write_b128 v132, v[116:119] offset:4672
	ds_write_b128 v132, v[120:123] offset:6912
	ds_write_b128 v132, v[124:127] offset:6976
	s_waitcnt lgkmcnt(0)
	ds_read_b128 v[96:99], v133
	ds_read_b128 v[100:103], v133 offset:16
	ds_read_b128 v[104:107], v133 offset:32
	ds_read_b128 v[108:111], v133 offset:48
	ds_read_b128 v[112:115], v133 offset:64
	ds_read_b128 v[116:119], v133 offset:80
	ds_read_b128 v[120:123], v133 offset:96
	ds_read_b128 v[124:127], v133 offset:112
	s_waitcnt lgkmcnt(0)
	v_mul_f32_e32 v128, v51, v53
	v_mul_f32_e32 v129, v50, v53
	v_fma_f32 v130, v50, v52, -v128
	v_fma_f32 v131, v51, v52, v129
	v_add_f32_e32 v52, v130, v96
	v_add_f32_e32 v53, v131, v112
	v_cvt_pk_bf16_f32 v144, v52, v53
	ds_write_b32 v67, v144
	v_mul_f32_e32 v128, v51, v53
	v_mul_f32_e32 v129, v50, v53
	v_fma_f32 v130, v50, v52, -v128
	v_fma_f32 v131, v51, v52, v129
	v_add_f32_e32 v52, v130, v97
	v_add_f32_e32 v53, v131, v113
	v_cvt_pk_bf16_f32 v144, v52, v53
	ds_write_b32 v67, v144 offset:272
	v_mul_f32_e32 v128, v51, v53
	v_mul_f32_e32 v129, v50, v53
	v_fma_f32 v130, v50, v52, -v128
	v_fma_f32 v131, v51, v52, v129
	v_add_f32_e32 v52, v130, v98
	v_add_f32_e32 v53, v131, v114
	v_cvt_pk_bf16_f32 v144, v52, v53
	ds_write_b32 v67, v144 offset:544
	v_mul_f32_e32 v128, v51, v53
	v_mul_f32_e32 v129, v50, v53
	v_fma_f32 v130, v50, v52, -v128
	v_fma_f32 v131, v51, v52, v129
	v_add_f32_e32 v52, v130, v99
	v_add_f32_e32 v53, v131, v115
	v_cvt_pk_bf16_f32 v144, v52, v53
	ds_write_b32 v67, v144 offset:816
	v_mul_f32_e32 v128, v51, v53
	v_mul_f32_e32 v129, v50, v53
	v_fma_f32 v130, v50, v52, -v128
	v_fma_f32 v131, v51, v52, v129
	v_add_f32_e32 v52, v130, v100
	v_add_f32_e32 v53, v131, v116
	v_cvt_pk_bf16_f32 v144, v52, v53
	ds_write_b32 v67, v144 offset:1088
	v_mul_f32_e32 v128, v51, v53
	v_mul_f32_e32 v129, v50, v53
	v_fma_f32 v130, v50, v52, -v128
	v_fma_f32 v131, v51, v52, v129
	v_add_f32_e32 v52, v130, v101
	v_add_f32_e32 v53, v131, v117
	v_cvt_pk_bf16_f32 v144, v52, v53
	ds_write_b32 v67, v144 offset:1360
	v_mul_f32_e32 v128, v51, v53
	v_mul_f32_e32 v129, v50, v53
	v_fma_f32 v130, v50, v52, -v128
	v_fma_f32 v131, v51, v52, v129
	v_add_f32_e32 v52, v130, v102
	v_add_f32_e32 v53, v131, v118
	v_cvt_pk_bf16_f32 v144, v52, v53
	ds_write_b32 v67, v144 offset:1632
	v_mul_f32_e32 v128, v51, v53
	v_mul_f32_e32 v129, v50, v53
	v_fma_f32 v130, v50, v52, -v128
	v_fma_f32 v131, v51, v52, v129
	v_add_f32_e32 v52, v130, v103
	v_add_f32_e32 v53, v131, v119
	v_cvt_pk_bf16_f32 v144, v52, v53
	ds_write_b32 v67, v144 offset:1904
	v_mul_f32_e32 v128, v51, v53
	v_mul_f32_e32 v129, v50, v53
	v_fma_f32 v130, v50, v52, -v128
	v_fma_f32 v131, v51, v52, v129
	v_add_f32_e32 v52, v130, v104
	v_add_f32_e32 v53, v131, v120
	v_cvt_pk_bf16_f32 v144, v52, v53
	ds_write_b32 v67, v144 offset:2176
	v_mul_f32_e32 v128, v51, v53
	v_mul_f32_e32 v129, v50, v53
	v_fma_f32 v130, v50, v52, -v128
	v_fma_f32 v131, v51, v52, v129
	v_add_f32_e32 v52, v130, v105
	v_add_f32_e32 v53, v131, v121
	v_cvt_pk_bf16_f32 v144, v52, v53
	ds_write_b32 v67, v144 offset:2448
	v_mul_f32_e32 v128, v51, v53
	v_mul_f32_e32 v129, v50, v53
	v_fma_f32 v130, v50, v52, -v128
	v_fma_f32 v131, v51, v52, v129
	v_add_f32_e32 v52, v130, v106
	v_add_f32_e32 v53, v131, v122
	v_cvt_pk_bf16_f32 v144, v52, v53
	ds_write_b32 v67, v144 offset:2720
	v_mul_f32_e32 v128, v51, v53
	v_mul_f32_e32 v129, v50, v53
	v_fma_f32 v130, v50, v52, -v128
	v_fma_f32 v131, v51, v52, v129
	v_add_f32_e32 v52, v130, v107
	v_add_f32_e32 v53, v131, v123
	v_cvt_pk_bf16_f32 v144, v52, v53
	ds_write_b32 v67, v144 offset:2992
	v_mul_f32_e32 v128, v51, v53
	v_mul_f32_e32 v129, v50, v53
	v_fma_f32 v130, v50, v52, -v128
	v_fma_f32 v131, v51, v52, v129
	v_add_f32_e32 v52, v130, v108
	v_add_f32_e32 v53, v131, v124
	v_cvt_pk_bf16_f32 v144, v52, v53
	ds_write_b32 v67, v144 offset:3264
	v_mul_f32_e32 v128, v51, v53
	v_mul_f32_e32 v129, v50, v53
	v_fma_f32 v130, v50, v52, -v128
	v_fma_f32 v131, v51, v52, v129
	v_add_f32_e32 v52, v130, v109
	v_add_f32_e32 v53, v131, v125
	v_cvt_pk_bf16_f32 v144, v52, v53
	ds_write_b32 v67, v144 offset:3536
	v_mul_f32_e32 v128, v51, v53
	v_mul_f32_e32 v129, v50, v53
	v_fma_f32 v130, v50, v52, -v128
	v_fma_f32 v131, v51, v52, v129
	v_add_f32_e32 v52, v130, v110
	v_add_f32_e32 v53, v131, v126
	v_cvt_pk_bf16_f32 v144, v52, v53
	ds_write_b32 v67, v144 offset:3808
	v_mul_f32_e32 v128, v51, v53
	v_mul_f32_e32 v129, v50, v53
	v_fma_f32 v130, v50, v52, -v128
	v_fma_f32 v131, v51, v52, v129
	v_add_f32_e32 v52, v130, v111
	v_add_f32_e32 v53, v131, v127
	v_cvt_pk_bf16_f32 v144, v52, v53
	ds_write_b32 v67, v144 offset:4080
	s_waitcnt lgkmcnt(0)
	ds_read_b128 v[72:75], v69
	ds_read_b128 v[76:79], v69 offset:64
	s_waitcnt lgkmcnt(1)
	v_mfma_f32_16x16x32_bf16 v[72:75], v[72:75], v[34:37], 0
	s_waitcnt lgkmcnt(0)
	v_mfma_f32_16x16x32_bf16 v[72:75], v[76:79], v[38:41], v[72:75]
	ds_read_b128 v[76:79], v69 offset:128
	s_waitcnt lgkmcnt(0)
	v_mfma_f32_16x16x32_bf16 v[72:75], v[76:79], v[42:45], v[72:75]
	ds_read_b128 v[76:79], v69 offset:192
	s_waitcnt lgkmcnt(0)
	v_mfma_f32_16x16x32_bf16 v[72:75], v[76:79], v[46:49], v[72:75]
	v_add_u32_e32 v70, 0, v65
	v_or_b32_e32 v76, v70, v62
	v_cmp_lt_i32_e64 s[4:5], s33, v76
	s_nop 1
	v_cndmask_b32_e64 v70, v205, v206, s[4:5]
	v_sub_u32_e32 v70, v70, v76
	v_cndmask_b32_e32 v70, v70, v76, vcc
	v_add_u32_e32 v70, v70, v64
	v_ashrrev_i32_e32 v71, 31, v70
	v_lshl_add_u64 v[70:71], v[70:71], 0, v[0:1]
	v_lshlrev_b64 v[70:71], 11, v[70:71]
	v_lshl_add_u64 v[70:71], v[56:57], 0, v[70:71]
	v_cmp_gt_i32_e64 s[4:5], s33, v76
	global_store_dword v[70:71], v72, off
	v_or_b32_e32 v70, 1, v76
	v_cndmask_b32_e64 v71, v206, v205, s[4:5]
	v_sub_u32_e32 v71, v71, v70
	v_cndmask_b32_e32 v70, v71, v70, vcc
	v_add_u32_e32 v70, v70, v64
	v_ashrrev_i32_e32 v71, 31, v70
	v_lshl_add_u64 v[70:71], v[70:71], 0, v[0:1]
	v_lshlrev_b64 v[70:71], 11, v[70:71]
	v_lshl_add_u64 v[70:71], v[56:57], 0, v[70:71]
	global_store_dword v[70:71], v73, off
	v_or_b32_e32 v70, 2, v76
	v_cmp_lt_i32_e64 s[4:5], s33, v70
	s_nop 1
	v_cndmask_b32_e64 v71, v205, v206, s[4:5]
	v_sub_u32_e32 v71, v71, v70
	v_cndmask_b32_e32 v70, v71, v70, vcc
	v_add_u32_e32 v70, v70, v64
	v_ashrrev_i32_e32 v71, 31, v70
	v_lshl_add_u64 v[70:71], v[70:71], 0, v[0:1]
	v_lshlrev_b64 v[70:71], 11, v[70:71]
	v_lshl_add_u64 v[70:71], v[56:57], 0, v[70:71]
	global_store_dword v[70:71], v74, off
	v_or_b32_e32 v70, 3, v76
	v_cmp_lt_i32_e64 s[4:5], s33, v70
	s_nop 1
	v_cndmask_b32_e64 v71, v205, v206, s[4:5]
	v_sub_u32_e32 v71, v71, v70
	v_cndmask_b32_e32 v70, v71, v70, vcc
	v_add_u32_e32 v70, v70, v64
	v_ashrrev_i32_e32 v71, 31, v70
	v_lshl_add_u64 v[70:71], v[70:71], 0, v[0:1]
	v_lshlrev_b64 v[70:71], 11, v[70:71]
	v_lshl_add_u64 v[70:71], v[56:57], 0, v[70:71]
	global_store_dword v[70:71], v75, off
	s_waitcnt vmcnt(6)
	v_mfma_f32_16x16x4_f32 v[96:99], v84, v2, 0
	v_mfma_f32_16x16x4_f32 v[100:103], v84, v3, 0
	v_mfma_f32_16x16x4_f32 v[104:107], v84, v10, 0
	v_mfma_f32_16x16x4_f32 v[108:111], v84, v11, 0
	v_mfma_f32_16x16x4_f32 v[112:115], v84, v18, 0
	v_mfma_f32_16x16x4_f32 v[116:119], v84, v19, 0
	v_mfma_f32_16x16x4_f32 v[120:123], v84, v26, 0
	v_mfma_f32_16x16x4_f32 v[124:127], v84, v27, 0
	v_mfma_f32_16x16x4_f32 v[96:99], v85, v4, v[96:99]
	v_mfma_f32_16x16x4_f32 v[100:103], v85, v5, v[100:103]
	v_mfma_f32_16x16x4_f32 v[104:107], v85, v12, v[104:107]
	v_mfma_f32_16x16x4_f32 v[108:111], v85, v13, v[108:111]
	v_mfma_f32_16x16x4_f32 v[112:115], v85, v20, v[112:115]
	v_mfma_f32_16x16x4_f32 v[116:119], v85, v21, v[116:119]
	v_mfma_f32_16x16x4_f32 v[120:123], v85, v28, v[120:123]
	v_mfma_f32_16x16x4_f32 v[124:127], v85, v29, v[124:127]
	v_mfma_f32_16x16x4_f32 v[96:99], v86, v6, v[96:99]
	v_mfma_f32_16x16x4_f32 v[100:103], v86, v7, v[100:103]
	v_mfma_f32_16x16x4_f32 v[104:107], v86, v14, v[104:107]
	v_mfma_f32_16x16x4_f32 v[108:111], v86, v15, v[108:111]
	v_mfma_f32_16x16x4_f32 v[112:115], v86, v22, v[112:115]
	v_mfma_f32_16x16x4_f32 v[116:119], v86, v23, v[116:119]
	v_mfma_f32_16x16x4_f32 v[120:123], v86, v30, v[120:123]
	v_mfma_f32_16x16x4_f32 v[124:127], v86, v31, v[124:127]
	v_mfma_f32_16x16x4_f32 v[96:99], v87, v8, v[96:99]
	v_mfma_f32_16x16x4_f32 v[100:103], v87, v9, v[100:103]
	v_mfma_f32_16x16x4_f32 v[104:107], v87, v16, v[104:107]
	v_mfma_f32_16x16x4_f32 v[108:111], v87, v17, v[108:111]
	v_mfma_f32_16x16x4_f32 v[112:115], v87, v24, v[112:115]
	v_mfma_f32_16x16x4_f32 v[116:119], v87, v25, v[116:119]
	v_mfma_f32_16x16x4_f32 v[120:123], v87, v32, v[120:123]
	v_mfma_f32_16x16x4_f32 v[124:127], v87, v33, v[124:127]
	s_nop 9
	ds_write_b128 v132, v[96:99]
	ds_write_b128 v132, v[100:103] offset:64
	ds_write_b128 v132, v[104:107] offset:2304
	ds_write_b128 v132, v[108:111] offset:2368
	ds_write_b128 v132, v[112:115] offset:4608
	ds_write_b128 v132, v[116:119] offset:4672
	ds_write_b128 v132, v[120:123] offset:6912
	ds_write_b128 v132, v[124:127] offset:6976
	s_waitcnt lgkmcnt(0)
	ds_read_b128 v[96:99], v133
	ds_read_b128 v[100:103], v133 offset:16
	ds_read_b128 v[104:107], v133 offset:32
	ds_read_b128 v[108:111], v133 offset:48
	ds_read_b128 v[112:115], v133 offset:64
	ds_read_b128 v[116:119], v133 offset:80
	ds_read_b128 v[120:123], v133 offset:96
	ds_read_b128 v[124:127], v133 offset:112
	s_waitcnt lgkmcnt(0)
	v_mul_f32_e32 v128, v51, v53
	v_mul_f32_e32 v129, v50, v53
	v_fma_f32 v130, v50, v52, -v128
	v_fma_f32 v131, v51, v52, v129
	v_add_f32_e32 v52, v130, v96
	v_add_f32_e32 v53, v131, v112
	v_cvt_pk_bf16_f32 v144, v52, v53
	ds_write_b32 v67, v144
	v_mul_f32_e32 v128, v51, v53
	v_mul_f32_e32 v129, v50, v53
	v_fma_f32 v130, v50, v52, -v128
	v_fma_f32 v131, v51, v52, v129
	v_add_f32_e32 v52, v130, v97
	v_add_f32_e32 v53, v131, v113
	v_cvt_pk_bf16_f32 v144, v52, v53
	ds_write_b32 v67, v144 offset:272
	v_mul_f32_e32 v128, v51, v53
	v_mul_f32_e32 v129, v50, v53
	v_fma_f32 v130, v50, v52, -v128
	v_fma_f32 v131, v51, v52, v129
	v_add_f32_e32 v52, v130, v98
	v_add_f32_e32 v53, v131, v114
	v_cvt_pk_bf16_f32 v144, v52, v53
	ds_write_b32 v67, v144 offset:544
	v_mul_f32_e32 v128, v51, v53
	v_mul_f32_e32 v129, v50, v53
	v_fma_f32 v130, v50, v52, -v128
	v_fma_f32 v131, v51, v52, v129
	v_add_f32_e32 v52, v130, v99
	v_add_f32_e32 v53, v131, v115
	v_cvt_pk_bf16_f32 v144, v52, v53
	ds_write_b32 v67, v144 offset:816
	v_mul_f32_e32 v128, v51, v53
	v_mul_f32_e32 v129, v50, v53
	v_fma_f32 v130, v50, v52, -v128
	v_fma_f32 v131, v51, v52, v129
	v_add_f32_e32 v52, v130, v100
	v_add_f32_e32 v53, v131, v116
	v_cvt_pk_bf16_f32 v144, v52, v53
	ds_write_b32 v67, v144 offset:1088
	v_mul_f32_e32 v128, v51, v53
	v_mul_f32_e32 v129, v50, v53
	v_fma_f32 v130, v50, v52, -v128
	v_fma_f32 v131, v51, v52, v129
	v_add_f32_e32 v52, v130, v101
	v_add_f32_e32 v53, v131, v117
	v_cvt_pk_bf16_f32 v144, v52, v53
	ds_write_b32 v67, v144 offset:1360
	v_mul_f32_e32 v128, v51, v53
	v_mul_f32_e32 v129, v50, v53
	v_fma_f32 v130, v50, v52, -v128
	v_fma_f32 v131, v51, v52, v129
	v_add_f32_e32 v52, v130, v102
	v_add_f32_e32 v53, v131, v118
	v_cvt_pk_bf16_f32 v144, v52, v53
	ds_write_b32 v67, v144 offset:1632
	v_mul_f32_e32 v128, v51, v53
	v_mul_f32_e32 v129, v50, v53
	v_fma_f32 v130, v50, v52, -v128
	v_fma_f32 v131, v51, v52, v129
	v_add_f32_e32 v52, v130, v103
	v_add_f32_e32 v53, v131, v119
	v_cvt_pk_bf16_f32 v144, v52, v53
	ds_write_b32 v67, v144 offset:1904
	v_mul_f32_e32 v128, v51, v53
	v_mul_f32_e32 v129, v50, v53
	v_fma_f32 v130, v50, v52, -v128
	v_fma_f32 v131, v51, v52, v129
	v_add_f32_e32 v52, v130, v104
	v_add_f32_e32 v53, v131, v120
	v_cvt_pk_bf16_f32 v144, v52, v53
	ds_write_b32 v67, v144 offset:2176
	v_mul_f32_e32 v128, v51, v53
	v_mul_f32_e32 v129, v50, v53
	v_fma_f32 v130, v50, v52, -v128
	v_fma_f32 v131, v51, v52, v129
	v_add_f32_e32 v52, v130, v105
	v_add_f32_e32 v53, v131, v121
	v_cvt_pk_bf16_f32 v144, v52, v53
	ds_write_b32 v67, v144 offset:2448
	v_mul_f32_e32 v128, v51, v53
	v_mul_f32_e32 v129, v50, v53
	v_fma_f32 v130, v50, v52, -v128
	v_fma_f32 v131, v51, v52, v129
	v_add_f32_e32 v52, v130, v106
	v_add_f32_e32 v53, v131, v122
	v_cvt_pk_bf16_f32 v144, v52, v53
	ds_write_b32 v67, v144 offset:2720
	v_mul_f32_e32 v128, v51, v53
	v_mul_f32_e32 v129, v50, v53
	v_fma_f32 v130, v50, v52, -v128
	v_fma_f32 v131, v51, v52, v129
	v_add_f32_e32 v52, v130, v107
	v_add_f32_e32 v53, v131, v123
	v_cvt_pk_bf16_f32 v144, v52, v53
	ds_write_b32 v67, v144 offset:2992
	v_mul_f32_e32 v128, v51, v53
	v_mul_f32_e32 v129, v50, v53
	v_fma_f32 v130, v50, v52, -v128
	v_fma_f32 v131, v51, v52, v129
	v_add_f32_e32 v52, v130, v108
	v_add_f32_e32 v53, v131, v124
	v_cvt_pk_bf16_f32 v144, v52, v53
	ds_write_b32 v67, v144 offset:3264
	v_mul_f32_e32 v128, v51, v53
	v_mul_f32_e32 v129, v50, v53
	v_fma_f32 v130, v50, v52, -v128
	v_fma_f32 v131, v51, v52, v129
	v_add_f32_e32 v52, v130, v109
	v_add_f32_e32 v53, v131, v125
	v_cvt_pk_bf16_f32 v144, v52, v53
	ds_write_b32 v67, v144 offset:3536
	v_mul_f32_e32 v128, v51, v53
	v_mul_f32_e32 v129, v50, v53
	v_fma_f32 v130, v50, v52, -v128
	v_fma_f32 v131, v51, v52, v129
	v_add_f32_e32 v52, v130, v110
	v_add_f32_e32 v53, v131, v126
	v_cvt_pk_bf16_f32 v144, v52, v53
	ds_write_b32 v67, v144 offset:3808
	v_mul_f32_e32 v128, v51, v53
	v_mul_f32_e32 v129, v50, v53
	v_fma_f32 v130, v50, v52, -v128
	v_fma_f32 v131, v51, v52, v129
	v_add_f32_e32 v52, v130, v111
	v_add_f32_e32 v53, v131, v127
	v_cvt_pk_bf16_f32 v144, v52, v53
	ds_write_b32 v67, v144 offset:4080
	s_waitcnt lgkmcnt(0)
	ds_read_b128 v[72:75], v69
	ds_read_b128 v[76:79], v69 offset:64
	s_waitcnt lgkmcnt(1)
	v_mfma_f32_16x16x32_bf16 v[72:75], v[72:75], v[34:37], 0
	s_waitcnt lgkmcnt(0)
	v_mfma_f32_16x16x32_bf16 v[72:75], v[76:79], v[38:41], v[72:75]
	ds_read_b128 v[76:79], v69 offset:128
	s_waitcnt lgkmcnt(0)
	v_mfma_f32_16x16x32_bf16 v[72:75], v[76:79], v[42:45], v[72:75]
	ds_read_b128 v[76:79], v69 offset:192
	s_waitcnt lgkmcnt(0)
	v_mfma_f32_16x16x32_bf16 v[72:75], v[76:79], v[46:49], v[72:75]
	v_add_u32_e32 v70, 16, v65
	v_or_b32_e32 v76, v70, v62
	v_cmp_lt_i32_e64 s[4:5], s33, v76
	s_nop 1
	v_cndmask_b32_e64 v70, v205, v206, s[4:5]
	v_sub_u32_e32 v70, v70, v76
	v_cndmask_b32_e32 v70, v70, v76, vcc
	v_add_u32_e32 v70, v70, v64
	v_ashrrev_i32_e32 v71, 31, v70
	v_lshl_add_u64 v[70:71], v[70:71], 0, v[0:1]
	v_lshlrev_b64 v[70:71], 11, v[70:71]
	v_lshl_add_u64 v[70:71], v[56:57], 0, v[70:71]
	v_cmp_gt_i32_e64 s[4:5], s33, v76
	global_store_dword v[70:71], v72, off
	v_or_b32_e32 v70, 1, v76
	v_cndmask_b32_e64 v71, v206, v205, s[4:5]
	v_sub_u32_e32 v71, v71, v70
	v_cndmask_b32_e32 v70, v71, v70, vcc
	v_add_u32_e32 v70, v70, v64
	v_ashrrev_i32_e32 v71, 31, v70
	v_lshl_add_u64 v[70:71], v[70:71], 0, v[0:1]
	v_lshlrev_b64 v[70:71], 11, v[70:71]
	v_lshl_add_u64 v[70:71], v[56:57], 0, v[70:71]
	global_store_dword v[70:71], v73, off
	v_or_b32_e32 v70, 2, v76
	v_cmp_lt_i32_e64 s[4:5], s33, v70
	s_nop 1
	v_cndmask_b32_e64 v71, v205, v206, s[4:5]
	v_sub_u32_e32 v71, v71, v70
	v_cndmask_b32_e32 v70, v71, v70, vcc
	v_add_u32_e32 v70, v70, v64
	v_ashrrev_i32_e32 v71, 31, v70
	v_lshl_add_u64 v[70:71], v[70:71], 0, v[0:1]
	v_lshlrev_b64 v[70:71], 11, v[70:71]
	v_lshl_add_u64 v[70:71], v[56:57], 0, v[70:71]
	global_store_dword v[70:71], v74, off
	v_or_b32_e32 v70, 3, v76
	v_cmp_lt_i32_e64 s[4:5], s33, v70
	s_nop 1
	v_cndmask_b32_e64 v71, v205, v206, s[4:5]
	v_sub_u32_e32 v71, v71, v70
	v_cndmask_b32_e32 v70, v71, v70, vcc
	v_add_u32_e32 v70, v70, v64
	v_ashrrev_i32_e32 v71, 31, v70
	v_lshl_add_u64 v[70:71], v[70:71], 0, v[0:1]
	v_lshlrev_b64 v[70:71], 11, v[70:71]
	v_lshl_add_u64 v[70:71], v[56:57], 0, v[70:71]
	global_store_dword v[70:71], v75, off
	s_waitcnt vmcnt(9)
	v_mfma_f32_16x16x4_f32 v[96:99], v88, v2, 0
	v_mfma_f32_16x16x4_f32 v[100:103], v88, v3, 0
	v_mfma_f32_16x16x4_f32 v[104:107], v88, v10, 0
	v_mfma_f32_16x16x4_f32 v[108:111], v88, v11, 0
	v_mfma_f32_16x16x4_f32 v[112:115], v88, v18, 0
	v_mfma_f32_16x16x4_f32 v[116:119], v88, v19, 0
	v_mfma_f32_16x16x4_f32 v[120:123], v88, v26, 0
	v_mfma_f32_16x16x4_f32 v[124:127], v88, v27, 0
	v_mfma_f32_16x16x4_f32 v[96:99], v89, v4, v[96:99]
	v_mfma_f32_16x16x4_f32 v[100:103], v89, v5, v[100:103]
	v_mfma_f32_16x16x4_f32 v[104:107], v89, v12, v[104:107]
	v_mfma_f32_16x16x4_f32 v[108:111], v89, v13, v[108:111]
	v_mfma_f32_16x16x4_f32 v[112:115], v89, v20, v[112:115]
	v_mfma_f32_16x16x4_f32 v[116:119], v89, v21, v[116:119]
	v_mfma_f32_16x16x4_f32 v[120:123], v89, v28, v[120:123]
	v_mfma_f32_16x16x4_f32 v[124:127], v89, v29, v[124:127]
	v_mfma_f32_16x16x4_f32 v[96:99], v90, v6, v[96:99]
	v_mfma_f32_16x16x4_f32 v[100:103], v90, v7, v[100:103]
	v_mfma_f32_16x16x4_f32 v[104:107], v90, v14, v[104:107]
	v_mfma_f32_16x16x4_f32 v[108:111], v90, v15, v[108:111]
	v_mfma_f32_16x16x4_f32 v[112:115], v90, v22, v[112:115]
	v_mfma_f32_16x16x4_f32 v[116:119], v90, v23, v[116:119]
	v_mfma_f32_16x16x4_f32 v[120:123], v90, v30, v[120:123]
	v_mfma_f32_16x16x4_f32 v[124:127], v90, v31, v[124:127]
	v_mfma_f32_16x16x4_f32 v[96:99], v91, v8, v[96:99]
	v_mfma_f32_16x16x4_f32 v[100:103], v91, v9, v[100:103]
	v_mfma_f32_16x16x4_f32 v[104:107], v91, v16, v[104:107]
	v_mfma_f32_16x16x4_f32 v[108:111], v91, v17, v[108:111]
	v_mfma_f32_16x16x4_f32 v[112:115], v91, v24, v[112:115]
	v_mfma_f32_16x16x4_f32 v[116:119], v91, v25, v[116:119]
	v_mfma_f32_16x16x4_f32 v[120:123], v91, v32, v[120:123]
	v_mfma_f32_16x16x4_f32 v[124:127], v91, v33, v[124:127]
	s_nop 9
	ds_write_b128 v132, v[96:99]
	ds_write_b128 v132, v[100:103] offset:64
	ds_write_b128 v132, v[104:107] offset:2304
	ds_write_b128 v132, v[108:111] offset:2368
	ds_write_b128 v132, v[112:115] offset:4608
	ds_write_b128 v132, v[116:119] offset:4672
	ds_write_b128 v132, v[120:123] offset:6912
	ds_write_b128 v132, v[124:127] offset:6976
	s_waitcnt lgkmcnt(0)
	ds_read_b128 v[96:99], v133
	ds_read_b128 v[100:103], v133 offset:16
	ds_read_b128 v[104:107], v133 offset:32
	ds_read_b128 v[108:111], v133 offset:48
	ds_read_b128 v[112:115], v133 offset:64
	ds_read_b128 v[116:119], v133 offset:80
	ds_read_b128 v[120:123], v133 offset:96
	ds_read_b128 v[124:127], v133 offset:112
	s_waitcnt lgkmcnt(0)
	v_mul_f32_e32 v128, v51, v53
	v_mul_f32_e32 v129, v50, v53
	v_fma_f32 v130, v50, v52, -v128
	v_fma_f32 v131, v51, v52, v129
	v_add_f32_e32 v52, v130, v96
	v_add_f32_e32 v53, v131, v112
	v_cvt_pk_bf16_f32 v144, v52, v53
	ds_write_b32 v67, v144
	v_mul_f32_e32 v128, v51, v53
	v_mul_f32_e32 v129, v50, v53
	v_fma_f32 v130, v50, v52, -v128
	v_fma_f32 v131, v51, v52, v129
	v_add_f32_e32 v52, v130, v97
	v_add_f32_e32 v53, v131, v113
	v_cvt_pk_bf16_f32 v144, v52, v53
	ds_write_b32 v67, v144 offset:272
	v_mul_f32_e32 v128, v51, v53
	v_mul_f32_e32 v129, v50, v53
	v_fma_f32 v130, v50, v52, -v128
	v_fma_f32 v131, v51, v52, v129
	v_add_f32_e32 v52, v130, v98
	v_add_f32_e32 v53, v131, v114
	v_cvt_pk_bf16_f32 v144, v52, v53
	ds_write_b32 v67, v144 offset:544
	v_mul_f32_e32 v128, v51, v53
	v_mul_f32_e32 v129, v50, v53
	v_fma_f32 v130, v50, v52, -v128
	v_fma_f32 v131, v51, v52, v129
	v_add_f32_e32 v52, v130, v99
	v_add_f32_e32 v53, v131, v115
	v_cvt_pk_bf16_f32 v144, v52, v53
	ds_write_b32 v67, v144 offset:816
	v_mul_f32_e32 v128, v51, v53
	v_mul_f32_e32 v129, v50, v53
	v_fma_f32 v130, v50, v52, -v128
	v_fma_f32 v131, v51, v52, v129
	v_add_f32_e32 v52, v130, v100
	v_add_f32_e32 v53, v131, v116
	v_cvt_pk_bf16_f32 v144, v52, v53
	ds_write_b32 v67, v144 offset:1088
	v_mul_f32_e32 v128, v51, v53
	v_mul_f32_e32 v129, v50, v53
	v_fma_f32 v130, v50, v52, -v128
	v_fma_f32 v131, v51, v52, v129
	v_add_f32_e32 v52, v130, v101
	v_add_f32_e32 v53, v131, v117
	v_cvt_pk_bf16_f32 v144, v52, v53
	ds_write_b32 v67, v144 offset:1360
	v_mul_f32_e32 v128, v51, v53
	v_mul_f32_e32 v129, v50, v53
	v_fma_f32 v130, v50, v52, -v128
	v_fma_f32 v131, v51, v52, v129
	v_add_f32_e32 v52, v130, v102
	v_add_f32_e32 v53, v131, v118
	v_cvt_pk_bf16_f32 v144, v52, v53
	ds_write_b32 v67, v144 offset:1632
	v_mul_f32_e32 v128, v51, v53
	v_mul_f32_e32 v129, v50, v53
	v_fma_f32 v130, v50, v52, -v128
	v_fma_f32 v131, v51, v52, v129
	v_add_f32_e32 v52, v130, v103
	v_add_f32_e32 v53, v131, v119
	v_cvt_pk_bf16_f32 v144, v52, v53
	ds_write_b32 v67, v144 offset:1904
	v_mul_f32_e32 v128, v51, v53
	v_mul_f32_e32 v129, v50, v53
	v_fma_f32 v130, v50, v52, -v128
	v_fma_f32 v131, v51, v52, v129
	v_add_f32_e32 v52, v130, v104
	v_add_f32_e32 v53, v131, v120
	v_cvt_pk_bf16_f32 v144, v52, v53
	ds_write_b32 v67, v144 offset:2176
	v_mul_f32_e32 v128, v51, v53
	v_mul_f32_e32 v129, v50, v53
	v_fma_f32 v130, v50, v52, -v128
	v_fma_f32 v131, v51, v52, v129
	v_add_f32_e32 v52, v130, v105
	v_add_f32_e32 v53, v131, v121
	v_cvt_pk_bf16_f32 v144, v52, v53
	ds_write_b32 v67, v144 offset:2448
	v_mul_f32_e32 v128, v51, v53
	v_mul_f32_e32 v129, v50, v53
	v_fma_f32 v130, v50, v52, -v128
	v_fma_f32 v131, v51, v52, v129
	v_add_f32_e32 v52, v130, v106
	v_add_f32_e32 v53, v131, v122
	v_cvt_pk_bf16_f32 v144, v52, v53
	ds_write_b32 v67, v144 offset:2720
	v_mul_f32_e32 v128, v51, v53
	v_mul_f32_e32 v129, v50, v53
	v_fma_f32 v130, v50, v52, -v128
	v_fma_f32 v131, v51, v52, v129
	v_add_f32_e32 v52, v130, v107
	v_add_f32_e32 v53, v131, v123
	v_cvt_pk_bf16_f32 v144, v52, v53
	ds_write_b32 v67, v144 offset:2992
	v_mul_f32_e32 v128, v51, v53
	v_mul_f32_e32 v129, v50, v53
	v_fma_f32 v130, v50, v52, -v128
	v_fma_f32 v131, v51, v52, v129
	v_add_f32_e32 v52, v130, v108
	v_add_f32_e32 v53, v131, v124
	v_cvt_pk_bf16_f32 v144, v52, v53
	ds_write_b32 v67, v144 offset:3264
	v_mul_f32_e32 v128, v51, v53
	v_mul_f32_e32 v129, v50, v53
	v_fma_f32 v130, v50, v52, -v128
	v_fma_f32 v131, v51, v52, v129
	v_add_f32_e32 v52, v130, v109
	v_add_f32_e32 v53, v131, v125
	v_cvt_pk_bf16_f32 v144, v52, v53
	ds_write_b32 v67, v144 offset:3536
	v_mul_f32_e32 v128, v51, v53
	v_mul_f32_e32 v129, v50, v53
	v_fma_f32 v130, v50, v52, -v128
	v_fma_f32 v131, v51, v52, v129
	v_add_f32_e32 v52, v130, v110
	v_add_f32_e32 v53, v131, v126
	v_cvt_pk_bf16_f32 v144, v52, v53
	ds_write_b32 v67, v144 offset:3808
	v_mul_f32_e32 v128, v51, v53
	v_mul_f32_e32 v129, v50, v53
	v_fma_f32 v130, v50, v52, -v128
	v_fma_f32 v131, v51, v52, v129
	v_add_f32_e32 v52, v130, v111
	v_add_f32_e32 v53, v131, v127
	v_cvt_pk_bf16_f32 v144, v52, v53
	ds_write_b32 v67, v144 offset:4080
	s_waitcnt lgkmcnt(0)
	ds_read_b128 v[72:75], v69
	ds_read_b128 v[76:79], v69 offset:64
	s_waitcnt lgkmcnt(1)
	v_mfma_f32_16x16x32_bf16 v[72:75], v[72:75], v[34:37], 0
	s_waitcnt lgkmcnt(0)
	v_mfma_f32_16x16x32_bf16 v[72:75], v[76:79], v[38:41], v[72:75]
	ds_read_b128 v[76:79], v69 offset:128
	s_waitcnt lgkmcnt(0)
	v_mfma_f32_16x16x32_bf16 v[72:75], v[76:79], v[42:45], v[72:75]
	ds_read_b128 v[76:79], v69 offset:192
	s_waitcnt lgkmcnt(0)
	v_mfma_f32_16x16x32_bf16 v[72:75], v[76:79], v[46:49], v[72:75]
	v_add_u32_e32 v70, 32, v65
	v_or_b32_e32 v76, v70, v62
	v_cmp_lt_i32_e64 s[4:5], s33, v76
	s_nop 1
	v_cndmask_b32_e64 v70, v205, v206, s[4:5]
	v_sub_u32_e32 v70, v70, v76
	v_cndmask_b32_e32 v70, v70, v76, vcc
	v_add_u32_e32 v70, v70, v64
	v_ashrrev_i32_e32 v71, 31, v70
	v_lshl_add_u64 v[70:71], v[70:71], 0, v[0:1]
	v_lshlrev_b64 v[70:71], 11, v[70:71]
	v_lshl_add_u64 v[70:71], v[56:57], 0, v[70:71]
	v_cmp_gt_i32_e64 s[4:5], s33, v76
	global_store_dword v[70:71], v72, off
	v_or_b32_e32 v70, 1, v76
	v_cndmask_b32_e64 v71, v206, v205, s[4:5]
	v_sub_u32_e32 v71, v71, v70
	v_cndmask_b32_e32 v70, v71, v70, vcc
	v_add_u32_e32 v70, v70, v64
	v_ashrrev_i32_e32 v71, 31, v70
	v_lshl_add_u64 v[70:71], v[70:71], 0, v[0:1]
	v_lshlrev_b64 v[70:71], 11, v[70:71]
	v_lshl_add_u64 v[70:71], v[56:57], 0, v[70:71]
	global_store_dword v[70:71], v73, off
	v_or_b32_e32 v70, 2, v76
	v_cmp_lt_i32_e64 s[4:5], s33, v70
	s_nop 1
	v_cndmask_b32_e64 v71, v205, v206, s[4:5]
	v_sub_u32_e32 v71, v71, v70
	v_cndmask_b32_e32 v70, v71, v70, vcc
	v_add_u32_e32 v70, v70, v64
	v_ashrrev_i32_e32 v71, 31, v70
	v_lshl_add_u64 v[70:71], v[70:71], 0, v[0:1]
	v_lshlrev_b64 v[70:71], 11, v[70:71]
	v_lshl_add_u64 v[70:71], v[56:57], 0, v[70:71]
	global_store_dword v[70:71], v74, off
	v_or_b32_e32 v70, 3, v76
	v_cmp_lt_i32_e64 s[4:5], s33, v70
	s_nop 1
	v_cndmask_b32_e64 v71, v205, v206, s[4:5]
	v_sub_u32_e32 v71, v71, v70
	v_cndmask_b32_e32 v70, v71, v70, vcc
	v_add_u32_e32 v70, v70, v64
	v_ashrrev_i32_e32 v71, 31, v70
	v_lshl_add_u64 v[70:71], v[70:71], 0, v[0:1]
	v_lshlrev_b64 v[70:71], 11, v[70:71]
	v_lshl_add_u64 v[70:71], v[56:57], 0, v[70:71]
	global_store_dword v[70:71], v75, off
	s_waitcnt vmcnt(12)
	v_mfma_f32_16x16x4_f32 v[96:99], v92, v2, 0
	v_mfma_f32_16x16x4_f32 v[100:103], v92, v3, 0
	v_mfma_f32_16x16x4_f32 v[104:107], v92, v10, 0
	v_mfma_f32_16x16x4_f32 v[108:111], v92, v11, 0
	v_mfma_f32_16x16x4_f32 v[112:115], v92, v18, 0
	v_mfma_f32_16x16x4_f32 v[116:119], v92, v19, 0
	v_mfma_f32_16x16x4_f32 v[120:123], v92, v26, 0
	v_mfma_f32_16x16x4_f32 v[124:127], v92, v27, 0
	v_mfma_f32_16x16x4_f32 v[96:99], v93, v4, v[96:99]
	v_mfma_f32_16x16x4_f32 v[100:103], v93, v5, v[100:103]
	v_mfma_f32_16x16x4_f32 v[104:107], v93, v12, v[104:107]
	v_mfma_f32_16x16x4_f32 v[108:111], v93, v13, v[108:111]
	v_mfma_f32_16x16x4_f32 v[112:115], v93, v20, v[112:115]
	v_mfma_f32_16x16x4_f32 v[116:119], v93, v21, v[116:119]
	v_mfma_f32_16x16x4_f32 v[120:123], v93, v28, v[120:123]
	v_mfma_f32_16x16x4_f32 v[124:127], v93, v29, v[124:127]
	v_mfma_f32_16x16x4_f32 v[96:99], v94, v6, v[96:99]
	v_mfma_f32_16x16x4_f32 v[100:103], v94, v7, v[100:103]
	v_mfma_f32_16x16x4_f32 v[104:107], v94, v14, v[104:107]
	v_mfma_f32_16x16x4_f32 v[108:111], v94, v15, v[108:111]
	v_mfma_f32_16x16x4_f32 v[112:115], v94, v22, v[112:115]
	v_mfma_f32_16x16x4_f32 v[116:119], v94, v23, v[116:119]
	v_mfma_f32_16x16x4_f32 v[120:123], v94, v30, v[120:123]
	v_mfma_f32_16x16x4_f32 v[124:127], v94, v31, v[124:127]
	v_mfma_f32_16x16x4_f32 v[96:99], v95, v8, v[96:99]
	v_mfma_f32_16x16x4_f32 v[100:103], v95, v9, v[100:103]
	v_mfma_f32_16x16x4_f32 v[104:107], v95, v16, v[104:107]
	v_mfma_f32_16x16x4_f32 v[108:111], v95, v17, v[108:111]
	v_mfma_f32_16x16x4_f32 v[112:115], v95, v24, v[112:115]
	v_mfma_f32_16x16x4_f32 v[116:119], v95, v25, v[116:119]
	v_mfma_f32_16x16x4_f32 v[120:123], v95, v32, v[120:123]
	v_mfma_f32_16x16x4_f32 v[124:127], v95, v33, v[124:127]
	s_nop 9
	ds_write_b128 v132, v[96:99]
	ds_write_b128 v132, v[100:103] offset:64
	ds_write_b128 v132, v[104:107] offset:2304
	ds_write_b128 v132, v[108:111] offset:2368
	ds_write_b128 v132, v[112:115] offset:4608
	ds_write_b128 v132, v[116:119] offset:4672
	ds_write_b128 v132, v[120:123] offset:6912
	ds_write_b128 v132, v[124:127] offset:6976
	s_waitcnt lgkmcnt(0)
	ds_read_b128 v[96:99], v133
	ds_read_b128 v[100:103], v133 offset:16
	ds_read_b128 v[104:107], v133 offset:32
	ds_read_b128 v[108:111], v133 offset:48
	ds_read_b128 v[112:115], v133 offset:64
	ds_read_b128 v[116:119], v133 offset:80
	ds_read_b128 v[120:123], v133 offset:96
	ds_read_b128 v[124:127], v133 offset:112
	s_waitcnt lgkmcnt(0)
	v_mul_f32_e32 v128, v51, v53
	v_mul_f32_e32 v129, v50, v53
	v_fma_f32 v130, v50, v52, -v128
	v_fma_f32 v131, v51, v52, v129
	v_add_f32_e32 v52, v130, v96
	v_add_f32_e32 v53, v131, v112
	v_cvt_pk_bf16_f32 v144, v52, v53
	ds_write_b32 v67, v144
	v_mul_f32_e32 v128, v51, v53
	v_mul_f32_e32 v129, v50, v53
	v_fma_f32 v130, v50, v52, -v128
	v_fma_f32 v131, v51, v52, v129
	v_add_f32_e32 v52, v130, v97
	v_add_f32_e32 v53, v131, v113
	v_cvt_pk_bf16_f32 v144, v52, v53
	ds_write_b32 v67, v144 offset:272
	v_mul_f32_e32 v128, v51, v53
	v_mul_f32_e32 v129, v50, v53
	v_fma_f32 v130, v50, v52, -v128
	v_fma_f32 v131, v51, v52, v129
	v_add_f32_e32 v52, v130, v98
	v_add_f32_e32 v53, v131, v114
	v_cvt_pk_bf16_f32 v144, v52, v53
	ds_write_b32 v67, v144 offset:544
	v_mul_f32_e32 v128, v51, v53
	v_mul_f32_e32 v129, v50, v53
	v_fma_f32 v130, v50, v52, -v128
	v_fma_f32 v131, v51, v52, v129
	v_add_f32_e32 v52, v130, v99
	v_add_f32_e32 v53, v131, v115
	v_cvt_pk_bf16_f32 v144, v52, v53
	ds_write_b32 v67, v144 offset:816
	v_mul_f32_e32 v128, v51, v53
	v_mul_f32_e32 v129, v50, v53
	v_fma_f32 v130, v50, v52, -v128
	v_fma_f32 v131, v51, v52, v129
	v_add_f32_e32 v52, v130, v100
	v_add_f32_e32 v53, v131, v116
	v_cvt_pk_bf16_f32 v144, v52, v53
	ds_write_b32 v67, v144 offset:1088
	v_mul_f32_e32 v128, v51, v53
	v_mul_f32_e32 v129, v50, v53
	v_fma_f32 v130, v50, v52, -v128
	v_fma_f32 v131, v51, v52, v129
	v_add_f32_e32 v52, v130, v101
	v_add_f32_e32 v53, v131, v117
	v_cvt_pk_bf16_f32 v144, v52, v53
	ds_write_b32 v67, v144 offset:1360
	v_mul_f32_e32 v128, v51, v53
	v_mul_f32_e32 v129, v50, v53
	v_fma_f32 v130, v50, v52, -v128
	v_fma_f32 v131, v51, v52, v129
	v_add_f32_e32 v52, v130, v102
	v_add_f32_e32 v53, v131, v118
	v_cvt_pk_bf16_f32 v144, v52, v53
	ds_write_b32 v67, v144 offset:1632
	v_mul_f32_e32 v128, v51, v53
	v_mul_f32_e32 v129, v50, v53
	v_fma_f32 v130, v50, v52, -v128
	v_fma_f32 v131, v51, v52, v129
	v_add_f32_e32 v52, v130, v103
	v_add_f32_e32 v53, v131, v119
	v_cvt_pk_bf16_f32 v144, v52, v53
	ds_write_b32 v67, v144 offset:1904
	v_mul_f32_e32 v128, v51, v53
	v_mul_f32_e32 v129, v50, v53
	v_fma_f32 v130, v50, v52, -v128
	v_fma_f32 v131, v51, v52, v129
	v_add_f32_e32 v52, v130, v104
	v_add_f32_e32 v53, v131, v120
	v_cvt_pk_bf16_f32 v144, v52, v53
	ds_write_b32 v67, v144 offset:2176
	v_mul_f32_e32 v128, v51, v53
	v_mul_f32_e32 v129, v50, v53
	v_fma_f32 v130, v50, v52, -v128
	v_fma_f32 v131, v51, v52, v129
	v_add_f32_e32 v52, v130, v105
	v_add_f32_e32 v53, v131, v121
	v_cvt_pk_bf16_f32 v144, v52, v53
	ds_write_b32 v67, v144 offset:2448
	v_mul_f32_e32 v128, v51, v53
	v_mul_f32_e32 v129, v50, v53
	v_fma_f32 v130, v50, v52, -v128
	v_fma_f32 v131, v51, v52, v129
	v_add_f32_e32 v52, v130, v106
	v_add_f32_e32 v53, v131, v122
	v_cvt_pk_bf16_f32 v144, v52, v53
	ds_write_b32 v67, v144 offset:2720
	v_mul_f32_e32 v128, v51, v53
	v_mul_f32_e32 v129, v50, v53
	v_fma_f32 v130, v50, v52, -v128
	v_fma_f32 v131, v51, v52, v129
	v_add_f32_e32 v52, v130, v107
	v_add_f32_e32 v53, v131, v123
	v_cvt_pk_bf16_f32 v144, v52, v53
	ds_write_b32 v67, v144 offset:2992
	v_mul_f32_e32 v128, v51, v53
	v_mul_f32_e32 v129, v50, v53
	v_fma_f32 v130, v50, v52, -v128
	v_fma_f32 v131, v51, v52, v129
	v_add_f32_e32 v52, v130, v108
	v_add_f32_e32 v53, v131, v124
	v_cvt_pk_bf16_f32 v144, v52, v53
	ds_write_b32 v67, v144 offset:3264
	v_mul_f32_e32 v128, v51, v53
	v_mul_f32_e32 v129, v50, v53
	v_fma_f32 v130, v50, v52, -v128
	v_fma_f32 v131, v51, v52, v129
	v_add_f32_e32 v52, v130, v109
	v_add_f32_e32 v53, v131, v125
	v_cvt_pk_bf16_f32 v144, v52, v53
	ds_write_b32 v67, v144 offset:3536
	v_mul_f32_e32 v128, v51, v53
	v_mul_f32_e32 v129, v50, v53
	v_fma_f32 v130, v50, v52, -v128
	v_fma_f32 v131, v51, v52, v129
	v_add_f32_e32 v52, v130, v110
	v_add_f32_e32 v53, v131, v126
	v_cvt_pk_bf16_f32 v144, v52, v53
	ds_write_b32 v67, v144 offset:3808
	v_mul_f32_e32 v128, v51, v53
	v_mul_f32_e32 v129, v50, v53
	v_fma_f32 v130, v50, v52, -v128
	v_fma_f32 v131, v51, v52, v129
	v_add_f32_e32 v52, v130, v111
	v_add_f32_e32 v53, v131, v127
	v_cvt_pk_bf16_f32 v144, v52, v53
	ds_write_b32 v67, v144 offset:4080
	s_waitcnt lgkmcnt(0)
	ds_read_b128 v[72:75], v69
	ds_read_b128 v[76:79], v69 offset:64
	s_waitcnt lgkmcnt(1)
	v_mfma_f32_16x16x32_bf16 v[72:75], v[72:75], v[34:37], 0
	s_waitcnt lgkmcnt(0)
	v_mfma_f32_16x16x32_bf16 v[72:75], v[76:79], v[38:41], v[72:75]
	ds_read_b128 v[76:79], v69 offset:128
	s_waitcnt lgkmcnt(0)
	v_mfma_f32_16x16x32_bf16 v[72:75], v[76:79], v[42:45], v[72:75]
	ds_read_b128 v[76:79], v69 offset:192
	s_waitcnt lgkmcnt(0)
	v_mfma_f32_16x16x32_bf16 v[72:75], v[76:79], v[46:49], v[72:75]
	v_add_u32_e32 v70, 48, v65
	v_or_b32_e32 v76, v70, v62
	v_cmp_lt_i32_e64 s[4:5], s33, v76
	s_nop 1
	v_cndmask_b32_e64 v70, v205, v206, s[4:5]
	v_sub_u32_e32 v70, v70, v76
	v_cndmask_b32_e32 v70, v70, v76, vcc
	v_add_u32_e32 v70, v70, v64
	v_ashrrev_i32_e32 v71, 31, v70
	v_lshl_add_u64 v[70:71], v[70:71], 0, v[0:1]
	v_lshlrev_b64 v[70:71], 11, v[70:71]
	v_lshl_add_u64 v[70:71], v[56:57], 0, v[70:71]
	v_cmp_gt_i32_e64 s[4:5], s33, v76
	global_store_dword v[70:71], v72, off
	v_or_b32_e32 v70, 1, v76
	v_cndmask_b32_e64 v71, v206, v205, s[4:5]
	v_sub_u32_e32 v71, v71, v70
	v_cndmask_b32_e32 v70, v71, v70, vcc
	v_add_u32_e32 v70, v70, v64
	v_ashrrev_i32_e32 v71, 31, v70
	v_lshl_add_u64 v[70:71], v[70:71], 0, v[0:1]
	v_lshlrev_b64 v[70:71], 11, v[70:71]
	v_lshl_add_u64 v[70:71], v[56:57], 0, v[70:71]
	global_store_dword v[70:71], v73, off
	v_or_b32_e32 v70, 2, v76
	v_cmp_lt_i32_e64 s[4:5], s33, v70
	s_nop 1
	v_cndmask_b32_e64 v71, v205, v206, s[4:5]
	v_sub_u32_e32 v71, v71, v70
	v_cndmask_b32_e32 v70, v71, v70, vcc
	v_add_u32_e32 v70, v70, v64
	v_ashrrev_i32_e32 v71, 31, v70
	v_lshl_add_u64 v[70:71], v[70:71], 0, v[0:1]
	v_lshlrev_b64 v[70:71], 11, v[70:71]
	v_lshl_add_u64 v[70:71], v[56:57], 0, v[70:71]
	global_store_dword v[70:71], v74, off
	v_or_b32_e32 v70, 3, v76
	v_cmp_lt_i32_e64 s[4:5], s33, v70
	s_nop 1
	v_cndmask_b32_e64 v71, v205, v206, s[4:5]
	v_sub_u32_e32 v71, v71, v70
	v_cndmask_b32_e32 v70, v71, v70, vcc
	v_add_u32_e32 v70, v70, v64
	v_ashrrev_i32_e32 v71, 31, v70
	v_lshl_add_u64 v[70:71], v[70:71], 0, v[0:1]
	v_lshlrev_b64 v[70:71], 11, v[70:71]
	v_lshl_add_u64 v[70:71], v[56:57], 0, v[70:71]
	global_store_dword v[70:71], v75, off
	s_add_i32 s2, s2, 1
	s_cmp_eq_u32 s2, 17
	s_cbranch_scc0 .LBB0_504

.LBB0_538:
	s_waitcnt vmcnt(1)
	v_mov_b32_e32 v10, v163
	v_lshl_add_u32 v0, s2, 8, v46
	v_bfe_u32 v35, v10, 6, 2
	v_or_b32_e32 v34, v35, v0
	s_mov_b32 s3, 0x3c3c3c4
	v_lshrrev_b32_e32 v11, 5, v34
	v_and_b32_e32 v12, 31, v34
	v_mul_hi_u32 v13, v11, s3
	v_mul_u32_u24_e32 v0, 0x44, v13
	v_sub_u32_e32 v11, v11, v0
	v_lshl_or_b32 v12, v13, 5, v12
	v_mul_u32_u24_e32 v12, 0x44, v12
	v_add_u32_e32 v34, v12, v11
	s_mov_b32 s3, 0x78787879
	v_mul_hi_i32 v11, v34, s3
	v_ashrrev_i32_e32 v0, 5, v11
	s_waitcnt lgkmcnt(0)
	v_lshrrev_b32_e32 v12, 31, v11
	v_add_u32_e32 v13, v0, v12
	s_movk_i32 s3, 0x44
	v_and_b32_e32 v41, 31, v13
	v_lshrrev_b32_e32 v0, 10, v11
	v_mul_lo_u32 v13, v13, s3
	v_add_u32_e32 v0, v0, v12
	v_sub_u32_e32 v13, v34, v13
	v_bfe_u32 v43, v10, 2, 4
	s_waitcnt vmcnt(0)
	v_and_b32_e32 v14, 1, v0
	v_lshl_or_b32 v48, v13, 6, v43
	v_and_b32_e32 v47, 63, v10
	v_lshlrev_b32_e32 v2, 11, v14
	v_lshlrev_b32_e32 v0, 6, v41
	v_lshlrev_b32_e32 v10, 2, v10
	v_cmp_lt_i32_e32 vcc, s33, v48
	v_or3_b32 v2, v2, v0, v47
	v_readlane_b32 s56, v252, 0
	v_readlane_b32 s40, v254, 55
	v_and_b32_e32 v42, 12, v10
	v_cndmask_b32_e32 v10, v205, v206, vcc
	v_lshlrev_b32_e32 v15, 3, v2
	v_and_b32_e32 v134, 48, v2
	v_lshlrev_b32_e32 v134, 1, v134
	v_and_b32_e32 v30, 0xffffffcf, v2
	v_lshl_or_b32 v30, v30, 7, v134
	v_add_u32_e32 v134, 0x1000, v30
	v_readlane_b32 s57, v252, 1
	v_readlane_b32 s54, v255, 5
	v_readlane_b32 s55, v255, 6
	v_ashrrev_i32_e32 v11, 11, v11
	v_sub_u32_e32 v10, v10, v48
	v_cmp_eq_u32_e32 vcc, 0, v14
	global_load_dwordx4 v[2:5], v30, s[56:57]
	global_load_dwordx4 v[6:9], v30, s[56:57] offset:16
	global_load_dwordx2 v[36:37], v15, s[54:55]
	v_add_u32_e32 v44, v11, v12
	v_cndmask_b32_e32 v10, v10, v48, vcc
	s_movk_i32 s3, 0x1100
	v_mad_i32_i24 v10, v44, s3, v10
	v_ashrrev_i32_e32 v11, 31, v10
	v_lshlrev_b64 v[10:11], 11, v[10:11]
	v_lshl_add_u64 v[10:11], s[72:73], 0, v[10:11]
	v_lshlrev_b32_e32 v38, 2, v42
	v_lshl_add_u64 v[10:11], v[10:11], 0, v[0:1]
	v_and_b32_e32 v138, 48, v163
	v_mov_b32_e32 v139, v1
	v_lshl_add_u64 v[136:137], s[72:73], 0, v[0:1]
	v_lshl_add_u64 v[136:137], v[136:137], 0, v[138:139]
	v_mov_b32_e32 v39, v1
	v_lshl_add_u64 v[10:11], v[10:11], 0, v[38:39]
	s_nop 0
	global_load_dwordx4 v[10:13], v30, s[56:57] offset:2048
	global_load_dwordx4 v[14:17], v30, s[56:57] offset:2064
	global_load_dwordx4 v[18:21], v134, s[56:57]
	global_load_dwordx4 v[22:25], v134, s[56:57] offset:16
	global_load_dwordx4 v[26:29], v134, s[56:57] offset:2048
	s_nop 0
	global_load_dwordx4 v[30:33], v134, s[56:57] offset:2064
	s_movk_i32 s4, 0x4880
	v_mad_u32_u24 v0, v35, s4, v222
	v_lshlrev_b32_e32 v39, 6, v43
	v_mov_b32_e32 v40, 0
	s_mov_b32 s3, 0
	v_mad_u32_u24 v35, v35, s4, v45
	v_add3_u32 v49, v0, v39, v38
	v_mul_i32_i24_e32 v50, 0x1100, v44
	v_lshlrev_b32_e32 v0, 4, v41
	v_mov_b32_e32 v44, 0
	v_readlane_b32 s58, v252, 2
	v_readlane_b32 s59, v252, 3
	v_readlane_b32 s60, v252, 4
	v_readlane_b32 s61, v252, 5
	v_readlane_b32 s62, v252, 6
	v_readlane_b32 s63, v252, 7
	v_readlane_b32 s64, v252, 8
	v_readlane_b32 s65, v252, 9
	v_readlane_b32 s66, v252, 10
	v_readlane_b32 s67, v252, 11
	v_readlane_b32 s68, v252, 12
	v_readlane_b32 s69, v252, 13
	v_readlane_b32 s70, v252, 14
	v_readlane_b32 s71, v252, 15
	v_readlane_b32 s41, v254, 56
	v_readlane_b32 s42, v254, 57
	v_readlane_b32 s43, v254, 58
	v_readlane_b32 s44, v254, 59
	v_readlane_b32 s45, v254, 60
	v_readlane_b32 s46, v254, 61
	v_readlane_b32 s47, v254, 62
	v_readlane_b32 s48, v254, 63
	v_readlane_b32 s49, v255, 0
	v_readlane_b32 s50, v255, 1
	v_readlane_b32 s51, v255, 2
	v_readlane_b32 s52, v255, 3
	v_readlane_b32 s53, v255, 4
	v_and_b32_e32 v140, 15, v163
	v_and_b32_e32 v141, 0xffffffc0, v48
	v_add_u32_e32 v135, 0, v141
	v_or_b32_e32 v135, v135, v140
	v_cmp_lt_i32_e64 s[4:5], s33, v135
	s_nop 1
	v_cndmask_b32_e64 v142, v205, v206, s[4:5]
	v_sub_u32_e32 v142, v142, v135
	v_cndmask_b32_e32 v135, v142, v135, vcc
	v_add_u32_e32 v142, v135, v50
	v_ashrrev_i32_e32 v143, 31, v142
	v_lshlrev_b64 v[142:143], 11, v[142:143]
	v_lshl_add_u64 v[142:143], v[136:137], 0, v[142:143]
	global_load_dwordx4 v[80:83], v[142:143], off
	v_add_u32_e32 v135, 16, v141
	v_or_b32_e32 v135, v135, v140
	v_cmp_lt_i32_e64 s[4:5], s33, v135
	s_nop 1
	v_cndmask_b32_e64 v142, v205, v206, s[4:5]
	v_sub_u32_e32 v142, v142, v135
	v_cndmask_b32_e32 v135, v142, v135, vcc
	v_add_u32_e32 v142, v135, v50
	v_ashrrev_i32_e32 v143, 31, v142
	v_lshlrev_b64 v[142:143], 11, v[142:143]
	v_lshl_add_u64 v[142:143], v[136:137], 0, v[142:143]
	global_load_dwordx4 v[84:87], v[142:143], off
	v_add_u32_e32 v135, 32, v141
	v_or_b32_e32 v135, v135, v140
	v_cmp_lt_i32_e64 s[4:5], s33, v135
	s_nop 1
	v_cndmask_b32_e64 v142, v205, v206, s[4:5]
	v_sub_u32_e32 v142, v142, v135
	v_cndmask_b32_e32 v135, v142, v135, vcc
	v_add_u32_e32 v142, v135, v50
	v_ashrrev_i32_e32 v143, 31, v142
	v_lshlrev_b64 v[142:143], 11, v[142:143]
	v_lshl_add_u64 v[142:143], v[136:137], 0, v[142:143]
	global_load_dwordx4 v[88:91], v[142:143], off
	v_add_u32_e32 v135, 48, v141
	v_or_b32_e32 v135, v135, v140
	v_cmp_lt_i32_e64 s[4:5], s33, v135
	s_nop 1
	v_cndmask_b32_e64 v142, v205, v206, s[4:5]
	v_sub_u32_e32 v142, v142, v135
	v_cndmask_b32_e32 v135, v142, v135, vcc
	v_add_u32_e32 v142, v135, v50
	v_ashrrev_i32_e32 v143, 31, v142
	v_lshlrev_b64 v[142:143], 11, v[142:143]
	v_lshl_add_u64 v[142:143], v[136:137], 0, v[142:143]
	global_load_dwordx4 v[92:95], v[142:143], off
	v_mov_b32_e32 v41, 0
	v_and_b32_e32 v132, 48, v163
	s_movk_i32 s3, 0x90
	v_mad_u32_u24 v132, v140, s3, v132
	v_add_u32_e32 v132, v132, v35
	v_add_u32_e32 v132, 0xffffcc80, v132
	v_mad_u32_u24 v133, v47, s3, v35
	v_add_u32_e32 v133, 0xffffcc80, v133
	s_waitcnt vmcnt(3)
	v_mfma_f32_16x16x4_f32 v[96:99], v80, v2, 0
	v_mfma_f32_16x16x4_f32 v[100:103], v80, v3, 0
	v_mfma_f32_16x16x4_f32 v[104:107], v80, v10, 0
	v_mfma_f32_16x16x4_f32 v[108:111], v80, v11, 0
	v_mfma_f32_16x16x4_f32 v[112:115], v80, v18, 0
	v_mfma_f32_16x16x4_f32 v[116:119], v80, v19, 0
	v_mfma_f32_16x16x4_f32 v[120:123], v80, v26, 0
	v_mfma_f32_16x16x4_f32 v[124:127], v80, v27, 0
	v_mfma_f32_16x16x4_f32 v[96:99], v81, v4, v[96:99]
	v_mfma_f32_16x16x4_f32 v[100:103], v81, v5, v[100:103]
	v_mfma_f32_16x16x4_f32 v[104:107], v81, v12, v[104:107]
	v_mfma_f32_16x16x4_f32 v[108:111], v81, v13, v[108:111]
	v_mfma_f32_16x16x4_f32 v[112:115], v81, v20, v[112:115]
	v_mfma_f32_16x16x4_f32 v[116:119], v81, v21, v[116:119]
	v_mfma_f32_16x16x4_f32 v[120:123], v81, v28, v[120:123]
	v_mfma_f32_16x16x4_f32 v[124:127], v81, v29, v[124:127]
	v_mfma_f32_16x16x4_f32 v[96:99], v82, v6, v[96:99]
	v_mfma_f32_16x16x4_f32 v[100:103], v82, v7, v[100:103]
	v_mfma_f32_16x16x4_f32 v[104:107], v82, v14, v[104:107]
	v_mfma_f32_16x16x4_f32 v[108:111], v82, v15, v[108:111]
	v_mfma_f32_16x16x4_f32 v[112:115], v82, v22, v[112:115]
	v_mfma_f32_16x16x4_f32 v[116:119], v82, v23, v[116:119]
	v_mfma_f32_16x16x4_f32 v[120:123], v82, v30, v[120:123]
	v_mfma_f32_16x16x4_f32 v[124:127], v82, v31, v[124:127]
	v_mfma_f32_16x16x4_f32 v[96:99], v83, v8, v[96:99]
	v_mfma_f32_16x16x4_f32 v[100:103], v83, v9, v[100:103]
	v_mfma_f32_16x16x4_f32 v[104:107], v83, v16, v[104:107]
	v_mfma_f32_16x16x4_f32 v[108:111], v83, v17, v[108:111]
	v_mfma_f32_16x16x4_f32 v[112:115], v83, v24, v[112:115]
	v_mfma_f32_16x16x4_f32 v[116:119], v83, v25, v[116:119]
	v_mfma_f32_16x16x4_f32 v[120:123], v83, v32, v[120:123]
	v_mfma_f32_16x16x4_f32 v[124:127], v83, v33, v[124:127]
	s_nop 9
	ds_write_b128 v132, v[96:99]
	ds_write_b128 v132, v[100:103] offset:64
	ds_write_b128 v132, v[104:107] offset:2304
	ds_write_b128 v132, v[108:111] offset:2368
	ds_write_b128 v132, v[112:115] offset:4608
	ds_write_b128 v132, v[116:119] offset:4672
	ds_write_b128 v132, v[120:123] offset:6912
	ds_write_b128 v132, v[124:127] offset:6976
	s_waitcnt lgkmcnt(0)
	ds_read_b128 v[96:99], v133
	ds_read_b128 v[100:103], v133 offset:16
	ds_read_b128 v[104:107], v133 offset:32
	ds_read_b128 v[108:111], v133 offset:48
	ds_read_b128 v[112:115], v133 offset:64
	ds_read_b128 v[116:119], v133 offset:80
	ds_read_b128 v[120:123], v133 offset:96
	ds_read_b128 v[124:127], v133 offset:112
	s_waitcnt lgkmcnt(0)
	v_mul_f32_e32 v128, v37, v41
	v_mul_f32_e32 v129, v36, v41
	v_fma_f32 v130, v36, v40, -v128
	v_fma_f32 v131, v37, v40, v129
	v_add_f32_e32 v40, v130, v96
	v_add_f32_e32 v41, v131, v112
	v_mul_f32_e32 v128, v37, v41
	v_mul_f32_e32 v129, v36, v41
	v_fma_f32 v130, v36, v40, -v128
	v_fma_f32 v131, v37, v40, v129
	v_add_f32_e32 v40, v130, v97
	v_add_f32_e32 v41, v131, v113
	v_mul_f32_e32 v128, v37, v41
	v_mul_f32_e32 v129, v36, v41
	v_fma_f32 v130, v36, v40, -v128
	v_fma_f32 v131, v37, v40, v129
	v_add_f32_e32 v40, v130, v98
	v_add_f32_e32 v41, v131, v114
	v_mul_f32_e32 v128, v37, v41
	v_mul_f32_e32 v129, v36, v41
	v_fma_f32 v130, v36, v40, -v128
	v_fma_f32 v131, v37, v40, v129
	v_add_f32_e32 v40, v130, v99
	v_add_f32_e32 v41, v131, v115
	v_mul_f32_e32 v128, v37, v41
	v_mul_f32_e32 v129, v36, v41
	v_fma_f32 v130, v36, v40, -v128
	v_fma_f32 v131, v37, v40, v129
	v_add_f32_e32 v40, v130, v100
	v_add_f32_e32 v41, v131, v116
	v_mul_f32_e32 v128, v37, v41
	v_mul_f32_e32 v129, v36, v41
	v_fma_f32 v130, v36, v40, -v128
	v_fma_f32 v131, v37, v40, v129
	v_add_f32_e32 v40, v130, v101
	v_add_f32_e32 v41, v131, v117
	v_mul_f32_e32 v128, v37, v41
	v_mul_f32_e32 v129, v36, v41
	v_fma_f32 v130, v36, v40, -v128
	v_fma_f32 v131, v37, v40, v129
	v_add_f32_e32 v40, v130, v102
	v_add_f32_e32 v41, v131, v118
	v_mul_f32_e32 v128, v37, v41
	v_mul_f32_e32 v129, v36, v41
	v_fma_f32 v130, v36, v40, -v128
	v_fma_f32 v131, v37, v40, v129
	v_add_f32_e32 v40, v130, v103
	v_add_f32_e32 v41, v131, v119
	v_mul_f32_e32 v128, v37, v41
	v_mul_f32_e32 v129, v36, v41
	v_fma_f32 v130, v36, v40, -v128
	v_fma_f32 v131, v37, v40, v129
	v_add_f32_e32 v40, v130, v104
	v_add_f32_e32 v41, v131, v120
	v_mul_f32_e32 v128, v37, v41
	v_mul_f32_e32 v129, v36, v41
	v_fma_f32 v130, v36, v40, -v128
	v_fma_f32 v131, v37, v40, v129
	v_add_f32_e32 v40, v130, v105
	v_add_f32_e32 v41, v131, v121
	v_mul_f32_e32 v128, v37, v41
	v_mul_f32_e32 v129, v36, v41
	v_fma_f32 v130, v36, v40, -v128
	v_fma_f32 v131, v37, v40, v129
	v_add_f32_e32 v40, v130, v106
	v_add_f32_e32 v41, v131, v122
	v_mul_f32_e32 v128, v37, v41
	v_mul_f32_e32 v129, v36, v41
	v_fma_f32 v130, v36, v40, -v128
	v_fma_f32 v131, v37, v40, v129
	v_add_f32_e32 v40, v130, v107
	v_add_f32_e32 v41, v131, v123
	v_mul_f32_e32 v128, v37, v41
	v_mul_f32_e32 v129, v36, v41
	v_fma_f32 v130, v36, v40, -v128
	v_fma_f32 v131, v37, v40, v129
	v_add_f32_e32 v40, v130, v108
	v_add_f32_e32 v41, v131, v124
	v_mul_f32_e32 v128, v37, v41
	v_mul_f32_e32 v129, v36, v41
	v_fma_f32 v130, v36, v40, -v128
	v_fma_f32 v131, v37, v40, v129
	v_add_f32_e32 v40, v130, v109
	v_add_f32_e32 v41, v131, v125
	v_mul_f32_e32 v128, v37, v41
	v_mul_f32_e32 v129, v36, v41
	v_fma_f32 v130, v36, v40, -v128
	v_fma_f32 v131, v37, v40, v129
	v_add_f32_e32 v40, v130, v110
	v_add_f32_e32 v41, v131, v126
	v_mul_f32_e32 v128, v37, v41
	v_mul_f32_e32 v129, v36, v41
	v_fma_f32 v130, v36, v40, -v128
	v_fma_f32 v131, v37, v40, v129
	v_add_f32_e32 v40, v130, v111
	v_add_f32_e32 v41, v131, v127
	s_waitcnt vmcnt(2)
	v_mfma_f32_16x16x4_f32 v[96:99], v84, v2, 0
	v_mfma_f32_16x16x4_f32 v[100:103], v84, v3, 0
	v_mfma_f32_16x16x4_f32 v[104:107], v84, v10, 0
	v_mfma_f32_16x16x4_f32 v[108:111], v84, v11, 0
	v_mfma_f32_16x16x4_f32 v[112:115], v84, v18, 0
	v_mfma_f32_16x16x4_f32 v[116:119], v84, v19, 0
	v_mfma_f32_16x16x4_f32 v[120:123], v84, v26, 0
	v_mfma_f32_16x16x4_f32 v[124:127], v84, v27, 0
	v_mfma_f32_16x16x4_f32 v[96:99], v85, v4, v[96:99]
	v_mfma_f32_16x16x4_f32 v[100:103], v85, v5, v[100:103]
	v_mfma_f32_16x16x4_f32 v[104:107], v85, v12, v[104:107]
	v_mfma_f32_16x16x4_f32 v[108:111], v85, v13, v[108:111]
	v_mfma_f32_16x16x4_f32 v[112:115], v85, v20, v[112:115]
	v_mfma_f32_16x16x4_f32 v[116:119], v85, v21, v[116:119]
	v_mfma_f32_16x16x4_f32 v[120:123], v85, v28, v[120:123]
	v_mfma_f32_16x16x4_f32 v[124:127], v85, v29, v[124:127]
	v_mfma_f32_16x16x4_f32 v[96:99], v86, v6, v[96:99]
	v_mfma_f32_16x16x4_f32 v[100:103], v86, v7, v[100:103]
	v_mfma_f32_16x16x4_f32 v[104:107], v86, v14, v[104:107]
	v_mfma_f32_16x16x4_f32 v[108:111], v86, v15, v[108:111]
	v_mfma_f32_16x16x4_f32 v[112:115], v86, v22, v[112:115]
	v_mfma_f32_16x16x4_f32 v[116:119], v86, v23, v[116:119]
	v_mfma_f32_16x16x4_f32 v[120:123], v86, v30, v[120:123]
	v_mfma_f32_16x16x4_f32 v[124:127], v86, v31, v[124:127]
	v_mfma_f32_16x16x4_f32 v[96:99], v87, v8, v[96:99]
	v_mfma_f32_16x16x4_f32 v[100:103], v87, v9, v[100:103]
	v_mfma_f32_16x16x4_f32 v[104:107], v87, v16, v[104:107]
	v_mfma_f32_16x16x4_f32 v[108:111], v87, v17, v[108:111]
	v_mfma_f32_16x16x4_f32 v[112:115], v87, v24, v[112:115]
	v_mfma_f32_16x16x4_f32 v[116:119], v87, v25, v[116:119]
	v_mfma_f32_16x16x4_f32 v[120:123], v87, v32, v[120:123]
	v_mfma_f32_16x16x4_f32 v[124:127], v87, v33, v[124:127]
	s_nop 9
	ds_write_b128 v132, v[96:99]
	ds_write_b128 v132, v[100:103] offset:64
	ds_write_b128 v132, v[104:107] offset:2304
	ds_write_b128 v132, v[108:111] offset:2368
	ds_write_b128 v132, v[112:115] offset:4608
	ds_write_b128 v132, v[116:119] offset:4672
	ds_write_b128 v132, v[120:123] offset:6912
	ds_write_b128 v132, v[124:127] offset:6976
	s_waitcnt lgkmcnt(0)
	ds_read_b128 v[96:99], v133
	ds_read_b128 v[100:103], v133 offset:16
	ds_read_b128 v[104:107], v133 offset:32
	ds_read_b128 v[108:111], v133 offset:48
	ds_read_b128 v[112:115], v133 offset:64
	ds_read_b128 v[116:119], v133 offset:80
	ds_read_b128 v[120:123], v133 offset:96
	ds_read_b128 v[124:127], v133 offset:112
	s_waitcnt lgkmcnt(0)
	v_mul_f32_e32 v128, v37, v41
	v_mul_f32_e32 v129, v36, v41
	v_fma_f32 v130, v36, v40, -v128
	v_fma_f32 v131, v37, v40, v129
	v_add_f32_e32 v40, v130, v96
	v_add_f32_e32 v41, v131, v112
	v_mul_f32_e32 v128, v37, v41
	v_mul_f32_e32 v129, v36, v41
	v_fma_f32 v130, v36, v40, -v128
	v_fma_f32 v131, v37, v40, v129
	v_add_f32_e32 v40, v130, v97
	v_add_f32_e32 v41, v131, v113
	v_mul_f32_e32 v128, v37, v41
	v_mul_f32_e32 v129, v36, v41
	v_fma_f32 v130, v36, v40, -v128
	v_fma_f32 v131, v37, v40, v129
	v_add_f32_e32 v40, v130, v98
	v_add_f32_e32 v41, v131, v114
	v_mul_f32_e32 v128, v37, v41
	v_mul_f32_e32 v129, v36, v41
	v_fma_f32 v130, v36, v40, -v128
	v_fma_f32 v131, v37, v40, v129
	v_add_f32_e32 v40, v130, v99
	v_add_f32_e32 v41, v131, v115
	v_mul_f32_e32 v128, v37, v41
	v_mul_f32_e32 v129, v36, v41
	v_fma_f32 v130, v36, v40, -v128
	v_fma_f32 v131, v37, v40, v129
	v_add_f32_e32 v40, v130, v100
	v_add_f32_e32 v41, v131, v116
	v_mul_f32_e32 v128, v37, v41
	v_mul_f32_e32 v129, v36, v41
	v_fma_f32 v130, v36, v40, -v128
	v_fma_f32 v131, v37, v40, v129
	v_add_f32_e32 v40, v130, v101
	v_add_f32_e32 v41, v131, v117
	v_mul_f32_e32 v128, v37, v41
	v_mul_f32_e32 v129, v36, v41
	v_fma_f32 v130, v36, v40, -v128
	v_fma_f32 v131, v37, v40, v129
	v_add_f32_e32 v40, v130, v102
	v_add_f32_e32 v41, v131, v118
	v_mul_f32_e32 v128, v37, v41
	v_mul_f32_e32 v129, v36, v41
	v_fma_f32 v130, v36, v40, -v128
	v_fma_f32 v131, v37, v40, v129
	v_add_f32_e32 v40, v130, v103
	v_add_f32_e32 v41, v131, v119
	v_mul_f32_e32 v128, v37, v41
	v_mul_f32_e32 v129, v36, v41
	v_fma_f32 v130, v36, v40, -v128
	v_fma_f32 v131, v37, v40, v129
	v_add_f32_e32 v40, v130, v104
	v_add_f32_e32 v41, v131, v120
	v_mul_f32_e32 v128, v37, v41
	v_mul_f32_e32 v129, v36, v41
	v_fma_f32 v130, v36, v40, -v128
	v_fma_f32 v131, v37, v40, v129
	v_add_f32_e32 v40, v130, v105
	v_add_f32_e32 v41, v131, v121
	v_mul_f32_e32 v128, v37, v41
	v_mul_f32_e32 v129, v36, v41
	v_fma_f32 v130, v36, v40, -v128
	v_fma_f32 v131, v37, v40, v129
	v_add_f32_e32 v40, v130, v106
	v_add_f32_e32 v41, v131, v122
	v_mul_f32_e32 v128, v37, v41
	v_mul_f32_e32 v129, v36, v41
	v_fma_f32 v130, v36, v40, -v128
	v_fma_f32 v131, v37, v40, v129
	v_add_f32_e32 v40, v130, v107
	v_add_f32_e32 v41, v131, v123
	v_mul_f32_e32 v128, v37, v41
	v_mul_f32_e32 v129, v36, v41
	v_fma_f32 v130, v36, v40, -v128
	v_fma_f32 v131, v37, v40, v129
	v_add_f32_e32 v40, v130, v108
	v_add_f32_e32 v41, v131, v124
	v_mul_f32_e32 v128, v37, v41
	v_mul_f32_e32 v129, v36, v41
	v_fma_f32 v130, v36, v40, -v128
	v_fma_f32 v131, v37, v40, v129
	v_add_f32_e32 v40, v130, v109
	v_add_f32_e32 v41, v131, v125
	v_mul_f32_e32 v128, v37, v41
	v_mul_f32_e32 v129, v36, v41
	v_fma_f32 v130, v36, v40, -v128
	v_fma_f32 v131, v37, v40, v129
	v_add_f32_e32 v40, v130, v110
	v_add_f32_e32 v41, v131, v126
	v_mul_f32_e32 v128, v37, v41
	v_mul_f32_e32 v129, v36, v41
	v_fma_f32 v130, v36, v40, -v128
	v_fma_f32 v131, v37, v40, v129
	v_add_f32_e32 v40, v130, v111
	v_add_f32_e32 v41, v131, v127
	s_waitcnt vmcnt(1)
	v_mfma_f32_16x16x4_f32 v[96:99], v88, v2, 0
	v_mfma_f32_16x16x4_f32 v[100:103], v88, v3, 0
	v_mfma_f32_16x16x4_f32 v[104:107], v88, v10, 0
	v_mfma_f32_16x16x4_f32 v[108:111], v88, v11, 0
	v_mfma_f32_16x16x4_f32 v[112:115], v88, v18, 0
	v_mfma_f32_16x16x4_f32 v[116:119], v88, v19, 0
	v_mfma_f32_16x16x4_f32 v[120:123], v88, v26, 0
	v_mfma_f32_16x16x4_f32 v[124:127], v88, v27, 0
	v_mfma_f32_16x16x4_f32 v[96:99], v89, v4, v[96:99]
	v_mfma_f32_16x16x4_f32 v[100:103], v89, v5, v[100:103]
	v_mfma_f32_16x16x4_f32 v[104:107], v89, v12, v[104:107]
	v_mfma_f32_16x16x4_f32 v[108:111], v89, v13, v[108:111]
	v_mfma_f32_16x16x4_f32 v[112:115], v89, v20, v[112:115]
	v_mfma_f32_16x16x4_f32 v[116:119], v89, v21, v[116:119]
	v_mfma_f32_16x16x4_f32 v[120:123], v89, v28, v[120:123]
	v_mfma_f32_16x16x4_f32 v[124:127], v89, v29, v[124:127]
	v_mfma_f32_16x16x4_f32 v[96:99], v90, v6, v[96:99]
	v_mfma_f32_16x16x4_f32 v[100:103], v90, v7, v[100:103]
	v_mfma_f32_16x16x4_f32 v[104:107], v90, v14, v[104:107]
	v_mfma_f32_16x16x4_f32 v[108:111], v90, v15, v[108:111]
	v_mfma_f32_16x16x4_f32 v[112:115], v90, v22, v[112:115]
	v_mfma_f32_16x16x4_f32 v[116:119], v90, v23, v[116:119]
	v_mfma_f32_16x16x4_f32 v[120:123], v90, v30, v[120:123]
	v_mfma_f32_16x16x4_f32 v[124:127], v90, v31, v[124:127]
	v_mfma_f32_16x16x4_f32 v[96:99], v91, v8, v[96:99]
	v_mfma_f32_16x16x4_f32 v[100:103], v91, v9, v[100:103]
	v_mfma_f32_16x16x4_f32 v[104:107], v91, v16, v[104:107]
	v_mfma_f32_16x16x4_f32 v[108:111], v91, v17, v[108:111]
	v_mfma_f32_16x16x4_f32 v[112:115], v91, v24, v[112:115]
	v_mfma_f32_16x16x4_f32 v[116:119], v91, v25, v[116:119]
	v_mfma_f32_16x16x4_f32 v[120:123], v91, v32, v[120:123]
	v_mfma_f32_16x16x4_f32 v[124:127], v91, v33, v[124:127]
	s_nop 9
	ds_write_b128 v132, v[96:99]
	ds_write_b128 v132, v[100:103] offset:64
	ds_write_b128 v132, v[104:107] offset:2304
	ds_write_b128 v132, v[108:111] offset:2368
	ds_write_b128 v132, v[112:115] offset:4608
	ds_write_b128 v132, v[116:119] offset:4672
	ds_write_b128 v132, v[120:123] offset:6912
	ds_write_b128 v132, v[124:127] offset:6976
	s_waitcnt lgkmcnt(0)
	ds_read_b128 v[96:99], v133
	ds_read_b128 v[100:103], v133 offset:16
	ds_read_b128 v[104:107], v133 offset:32
	ds_read_b128 v[108:111], v133 offset:48
	ds_read_b128 v[112:115], v133 offset:64
	ds_read_b128 v[116:119], v133 offset:80
	ds_read_b128 v[120:123], v133 offset:96
	ds_read_b128 v[124:127], v133 offset:112
	s_waitcnt lgkmcnt(0)
	v_mul_f32_e32 v128, v37, v41
	v_mul_f32_e32 v129, v36, v41
	v_fma_f32 v130, v36, v40, -v128
	v_fma_f32 v131, v37, v40, v129
	v_add_f32_e32 v40, v130, v96
	v_add_f32_e32 v41, v131, v112
	v_mul_f32_e32 v128, v37, v41
	v_mul_f32_e32 v129, v36, v41
	v_fma_f32 v130, v36, v40, -v128
	v_fma_f32 v131, v37, v40, v129
	v_add_f32_e32 v40, v130, v97
	v_add_f32_e32 v41, v131, v113
	v_mul_f32_e32 v128, v37, v41
	v_mul_f32_e32 v129, v36, v41
	v_fma_f32 v130, v36, v40, -v128
	v_fma_f32 v131, v37, v40, v129
	v_add_f32_e32 v40, v130, v98
	v_add_f32_e32 v41, v131, v114
	v_mul_f32_e32 v128, v37, v41
	v_mul_f32_e32 v129, v36, v41
	v_fma_f32 v130, v36, v40, -v128
	v_fma_f32 v131, v37, v40, v129
	v_add_f32_e32 v40, v130, v99
	v_add_f32_e32 v41, v131, v115
	v_mul_f32_e32 v128, v37, v41
	v_mul_f32_e32 v129, v36, v41
	v_fma_f32 v130, v36, v40, -v128
	v_fma_f32 v131, v37, v40, v129
	v_add_f32_e32 v40, v130, v100
	v_add_f32_e32 v41, v131, v116
	v_mul_f32_e32 v128, v37, v41
	v_mul_f32_e32 v129, v36, v41
	v_fma_f32 v130, v36, v40, -v128
	v_fma_f32 v131, v37, v40, v129
	v_add_f32_e32 v40, v130, v101
	v_add_f32_e32 v41, v131, v117
	v_mul_f32_e32 v128, v37, v41
	v_mul_f32_e32 v129, v36, v41
	v_fma_f32 v130, v36, v40, -v128
	v_fma_f32 v131, v37, v40, v129
	v_add_f32_e32 v40, v130, v102
	v_add_f32_e32 v41, v131, v118
	v_mul_f32_e32 v128, v37, v41
	v_mul_f32_e32 v129, v36, v41
	v_fma_f32 v130, v36, v40, -v128
	v_fma_f32 v131, v37, v40, v129
	v_add_f32_e32 v40, v130, v103
	v_add_f32_e32 v41, v131, v119
	v_mul_f32_e32 v128, v37, v41
	v_mul_f32_e32 v129, v36, v41
	v_fma_f32 v130, v36, v40, -v128
	v_fma_f32 v131, v37, v40, v129
	v_add_f32_e32 v40, v130, v104
	v_add_f32_e32 v41, v131, v120
	v_mul_f32_e32 v128, v37, v41
	v_mul_f32_e32 v129, v36, v41
	v_fma_f32 v130, v36, v40, -v128
	v_fma_f32 v131, v37, v40, v129
	v_add_f32_e32 v40, v130, v105
	v_add_f32_e32 v41, v131, v121
	v_mul_f32_e32 v128, v37, v41
	v_mul_f32_e32 v129, v36, v41
	v_fma_f32 v130, v36, v40, -v128
	v_fma_f32 v131, v37, v40, v129
	v_add_f32_e32 v40, v130, v106
	v_add_f32_e32 v41, v131, v122
	v_mul_f32_e32 v128, v37, v41
	v_mul_f32_e32 v129, v36, v41
	v_fma_f32 v130, v36, v40, -v128
	v_fma_f32 v131, v37, v40, v129
	v_add_f32_e32 v40, v130, v107
	v_add_f32_e32 v41, v131, v123
	v_mul_f32_e32 v128, v37, v41
	v_mul_f32_e32 v129, v36, v41
	v_fma_f32 v130, v36, v40, -v128
	v_fma_f32 v131, v37, v40, v129
	v_add_f32_e32 v40, v130, v108
	v_add_f32_e32 v41, v131, v124
	v_mul_f32_e32 v128, v37, v41
	v_mul_f32_e32 v129, v36, v41
	v_fma_f32 v130, v36, v40, -v128
	v_fma_f32 v131, v37, v40, v129
	v_add_f32_e32 v40, v130, v109
	v_add_f32_e32 v41, v131, v125
	v_mul_f32_e32 v128, v37, v41
	v_mul_f32_e32 v129, v36, v41
	v_fma_f32 v130, v36, v40, -v128
	v_fma_f32 v131, v37, v40, v129
	v_add_f32_e32 v40, v130, v110
	v_add_f32_e32 v41, v131, v126
	v_mul_f32_e32 v128, v37, v41
	v_mul_f32_e32 v129, v36, v41
	v_fma_f32 v130, v36, v40, -v128
	v_fma_f32 v131, v37, v40, v129
	v_add_f32_e32 v40, v130, v111
	v_add_f32_e32 v41, v131, v127
	s_waitcnt vmcnt(0)
	v_mfma_f32_16x16x4_f32 v[96:99], v92, v2, 0
	v_mfma_f32_16x16x4_f32 v[100:103], v92, v3, 0
	v_mfma_f32_16x16x4_f32 v[104:107], v92, v10, 0
	v_mfma_f32_16x16x4_f32 v[108:111], v92, v11, 0
	v_mfma_f32_16x16x4_f32 v[112:115], v92, v18, 0
	v_mfma_f32_16x16x4_f32 v[116:119], v92, v19, 0
	v_mfma_f32_16x16x4_f32 v[120:123], v92, v26, 0
	v_mfma_f32_16x16x4_f32 v[124:127], v92, v27, 0
	v_mfma_f32_16x16x4_f32 v[96:99], v93, v4, v[96:99]
	v_mfma_f32_16x16x4_f32 v[100:103], v93, v5, v[100:103]
	v_mfma_f32_16x16x4_f32 v[104:107], v93, v12, v[104:107]
	v_mfma_f32_16x16x4_f32 v[108:111], v93, v13, v[108:111]
	v_mfma_f32_16x16x4_f32 v[112:115], v93, v20, v[112:115]
	v_mfma_f32_16x16x4_f32 v[116:119], v93, v21, v[116:119]
	v_mfma_f32_16x16x4_f32 v[120:123], v93, v28, v[120:123]
	v_mfma_f32_16x16x4_f32 v[124:127], v93, v29, v[124:127]
	v_mfma_f32_16x16x4_f32 v[96:99], v94, v6, v[96:99]
	v_mfma_f32_16x16x4_f32 v[100:103], v94, v7, v[100:103]
	v_mfma_f32_16x16x4_f32 v[104:107], v94, v14, v[104:107]
	v_mfma_f32_16x16x4_f32 v[108:111], v94, v15, v[108:111]
	v_mfma_f32_16x16x4_f32 v[112:115], v94, v22, v[112:115]
	v_mfma_f32_16x16x4_f32 v[116:119], v94, v23, v[116:119]
	v_mfma_f32_16x16x4_f32 v[120:123], v94, v30, v[120:123]
	v_mfma_f32_16x16x4_f32 v[124:127], v94, v31, v[124:127]
	v_mfma_f32_16x16x4_f32 v[96:99], v95, v8, v[96:99]
	v_mfma_f32_16x16x4_f32 v[100:103], v95, v9, v[100:103]
	v_mfma_f32_16x16x4_f32 v[104:107], v95, v16, v[104:107]
	v_mfma_f32_16x16x4_f32 v[108:111], v95, v17, v[108:111]
	v_mfma_f32_16x16x4_f32 v[112:115], v95, v24, v[112:115]
	v_mfma_f32_16x16x4_f32 v[116:119], v95, v25, v[116:119]
	v_mfma_f32_16x16x4_f32 v[120:123], v95, v32, v[120:123]
	v_mfma_f32_16x16x4_f32 v[124:127], v95, v33, v[124:127]
	s_nop 9
	ds_write_b128 v132, v[96:99]
	ds_write_b128 v132, v[100:103] offset:64
	ds_write_b128 v132, v[104:107] offset:2304
	ds_write_b128 v132, v[108:111] offset:2368
	ds_write_b128 v132, v[112:115] offset:4608
	ds_write_b128 v132, v[116:119] offset:4672
	ds_write_b128 v132, v[120:123] offset:6912
	ds_write_b128 v132, v[124:127] offset:6976
	s_waitcnt lgkmcnt(0)
	ds_read_b128 v[96:99], v133
	ds_read_b128 v[100:103], v133 offset:16
	ds_read_b128 v[104:107], v133 offset:32
	ds_read_b128 v[108:111], v133 offset:48
	ds_read_b128 v[112:115], v133 offset:64
	ds_read_b128 v[116:119], v133 offset:80
	ds_read_b128 v[120:123], v133 offset:96
	ds_read_b128 v[124:127], v133 offset:112
	s_waitcnt lgkmcnt(0)
	v_mul_f32_e32 v128, v37, v41
	v_mul_f32_e32 v129, v36, v41
	v_fma_f32 v130, v36, v40, -v128
	v_fma_f32 v131, v37, v40, v129
	v_add_f32_e32 v40, v130, v96
	v_add_f32_e32 v41, v131, v112
	v_mul_f32_e32 v128, v37, v41
	v_mul_f32_e32 v129, v36, v41
	v_fma_f32 v130, v36, v40, -v128
	v_fma_f32 v131, v37, v40, v129
	v_add_f32_e32 v40, v130, v97
	v_add_f32_e32 v41, v131, v113
	v_mul_f32_e32 v128, v37, v41
	v_mul_f32_e32 v129, v36, v41
	v_fma_f32 v130, v36, v40, -v128
	v_fma_f32 v131, v37, v40, v129
	v_add_f32_e32 v40, v130, v98
	v_add_f32_e32 v41, v131, v114
	v_mul_f32_e32 v128, v37, v41
	v_mul_f32_e32 v129, v36, v41
	v_fma_f32 v130, v36, v40, -v128
	v_fma_f32 v131, v37, v40, v129
	v_add_f32_e32 v40, v130, v99
	v_add_f32_e32 v41, v131, v115
	v_mul_f32_e32 v128, v37, v41
	v_mul_f32_e32 v129, v36, v41
	v_fma_f32 v130, v36, v40, -v128
	v_fma_f32 v131, v37, v40, v129
	v_add_f32_e32 v40, v130, v100
	v_add_f32_e32 v41, v131, v116
	v_mul_f32_e32 v128, v37, v41
	v_mul_f32_e32 v129, v36, v41
	v_fma_f32 v130, v36, v40, -v128
	v_fma_f32 v131, v37, v40, v129
	v_add_f32_e32 v40, v130, v101
	v_add_f32_e32 v41, v131, v117
	v_mul_f32_e32 v128, v37, v41
	v_mul_f32_e32 v129, v36, v41
	v_fma_f32 v130, v36, v40, -v128
	v_fma_f32 v131, v37, v40, v129
	v_add_f32_e32 v40, v130, v102
	v_add_f32_e32 v41, v131, v118
	v_mul_f32_e32 v128, v37, v41
	v_mul_f32_e32 v129, v36, v41
	v_fma_f32 v130, v36, v40, -v128
	v_fma_f32 v131, v37, v40, v129
	v_add_f32_e32 v40, v130, v103
	v_add_f32_e32 v41, v131, v119
	v_mul_f32_e32 v128, v37, v41
	v_mul_f32_e32 v129, v36, v41
	v_fma_f32 v130, v36, v40, -v128
	v_fma_f32 v131, v37, v40, v129
	v_add_f32_e32 v40, v130, v104
	v_add_f32_e32 v41, v131, v120
	v_mul_f32_e32 v128, v37, v41
	v_mul_f32_e32 v129, v36, v41
	v_fma_f32 v130, v36, v40, -v128
	v_fma_f32 v131, v37, v40, v129
	v_add_f32_e32 v40, v130, v105
	v_add_f32_e32 v41, v131, v121
	v_mul_f32_e32 v128, v37, v41
	v_mul_f32_e32 v129, v36, v41
	v_fma_f32 v130, v36, v40, -v128
	v_fma_f32 v131, v37, v40, v129
	v_add_f32_e32 v40, v130, v106
	v_add_f32_e32 v41, v131, v122
	v_mul_f32_e32 v128, v37, v41
	v_mul_f32_e32 v129, v36, v41
	v_fma_f32 v130, v36, v40, -v128
	v_fma_f32 v131, v37, v40, v129
	v_add_f32_e32 v40, v130, v107
	v_add_f32_e32 v41, v131, v123
	v_mul_f32_e32 v128, v37, v41
	v_mul_f32_e32 v129, v36, v41
	v_fma_f32 v130, v36, v40, -v128
	v_fma_f32 v131, v37, v40, v129
	v_add_f32_e32 v40, v130, v108
	v_add_f32_e32 v41, v131, v124
	v_mul_f32_e32 v128, v37, v41
	v_mul_f32_e32 v129, v36, v41
	v_fma_f32 v130, v36, v40, -v128
	v_fma_f32 v131, v37, v40, v129
	v_add_f32_e32 v40, v130, v109
	v_add_f32_e32 v41, v131, v125
	v_mul_f32_e32 v128, v37, v41
	v_mul_f32_e32 v129, v36, v41
	v_fma_f32 v130, v36, v40, -v128
	v_fma_f32 v131, v37, v40, v129
	v_add_f32_e32 v40, v130, v110
	v_add_f32_e32 v41, v131, v126
	v_mul_f32_e32 v128, v37, v41
	v_mul_f32_e32 v129, v36, v41
	v_fma_f32 v130, v36, v40, -v128
	v_fma_f32 v131, v37, v40, v129
	v_add_f32_e32 v40, v130, v111
	v_add_f32_e32 v41, v131, v127
	v_readlane_b32 s40, v252, 16
	v_readlane_b32 s41, v252, 17
	v_readlane_b32 s42, v252, 18
	v_readlane_b32 s43, v252, 19
	v_readlane_b32 s44, v252, 20
	v_readlane_b32 s45, v252, 21
	v_readlane_b32 s46, v252, 22
	v_readlane_b32 s47, v252, 23
	v_readlane_b32 s48, v252, 24
	v_readlane_b32 s49, v252, 25
	v_readlane_b32 s50, v252, 26
	v_readlane_b32 s51, v252, 27
	v_readlane_b32 s52, v252, 28
	v_readlane_b32 s53, v252, 29
	v_readlane_b32 s54, v252, 30
	v_readlane_b32 s55, v252, 31
	v_ashrrev_i32_e32 v35, 31, v34
	v_readlane_b32 s68, v252, 16
	v_lshlrev_b64 v[2:3], 9, v[34:35]
	v_readlane_b32 s76, v252, 24
	v_readlane_b32 s77, v252, 25
	v_lshlrev_b32_e32 v0, 3, v47
	s_add_i32 s2, s2, 1
	v_lshl_add_u64 v[2:3], s[76:77], 0, v[2:3]
	v_readlane_b32 s72, v252, 20
	v_readlane_b32 s73, v252, 21
	v_lshl_add_u64 v[2:3], v[2:3], 0, v[0:1]
	s_cmp_eq_u32 s2, 17
	v_readlane_b32 s69, v252, 17
	v_readlane_b32 s70, v252, 18
	v_readlane_b32 s71, v252, 19
	v_readlane_b32 s74, v252, 22
	v_readlane_b32 s75, v252, 23
	v_readlane_b32 s78, v252, 26
	v_readlane_b32 s79, v252, 27
	v_readlane_b32 s80, v252, 28
	v_readlane_b32 s81, v252, 29
	v_readlane_b32 s82, v252, 30
	v_readlane_b32 s83, v252, 31
	global_store_dwordx2 v[2:3], v[40:41], off
	s_cbranch_scc0 .LBB0_538
